# hand-written LayerNorm item body: gain/bias hoisted to registers, 3 rows in flight per wave, DPP wave reduction
# speedup vs baseline: 1.0239x; 1.0064x over previous
; DI void ln_finish(const Params& p, float* __restrict__ pr, const float4 (&v)[8], int lane) {
;     ...
; #pragma unroll
;   for (int i = 0; i < 8; ++i) {
;     const int c0 = (i * 64 + lane) * 4;
;     const float4 g = *reinterpret_cast<const float4*>(p.ln_g + c0);
;     const float4 bb = *reinterpret_cast<const float4*>(p.ln_b + c0);
; __device__ void phaseD_handoff(const Params& p, unsigned char* smem) {
;   int tidd = threadIdx.x; asm volatile("" : "+v"(tidd));
;   const int lane = tidd & 63, w = __builtin_amdgcn_readfirstlane(tidd >> 6);
;   int* s_item = reinterpret_cast<int*>(smem);
;   for (;;) {
;     if (tidd == 0) *s_item = atomicAdd(p.lnready + 2, 1);
;     __syncthreads();
;     const int it = *s_item;
;     __syncthreads();
;     if (it >= 130 * 4) break;
;     const int panel = it >> 2, chunk = it & 3;
;     if (w == 0) {
;       const int* flag = p.lnready + (panel < 128 ? 0 : 1);
;       const int need = panel < 128 ? 2048 : 16;
;       while (__hip_atomic_load(flag, __ATOMIC_RELAXED, __HIP_MEMORY_SCOPE_AGENT) < need) __builtin_amdgcn_s_sleep(8);
;       __builtin_amdgcn_fence(__ATOMIC_ACQUIRE, "agent");
;       asm volatile("s_waitcnt vmcnt(0)" ::: "memory");
;     }
;     __syncthreads();
;     const int row0 = panel * 256 + chunk * 64 + w * 8;
.LBB0_658:
	s_or_b64 exec, exec, s[0:1]
	s_barrier
	v_mov_b32_e32 v65, 0
	v_lshlrev_b32_e32 v0, 4, v160
	v_and_b32_e32 v64, 0x3f0, v0
	v_or_b32_e32 v0, 0x1000, v64
	v_mov_b32_e32 v1, v65
	v_readfirstlane_b32 s4, v160
	v_lshl_add_u64 v[70:71], s[40:41], 0, v[0:1]
	v_lshl_add_u64 v[72:73], s[42:43], 0, v[0:1]
	v_or_b32_e32 v0, 0x1400, v64
	s_cmp_lt_u32 s4, 64
	v_lshl_add_u64 v[74:75], s[40:41], 0, v[0:1]
	v_lshl_add_u64 v[76:77], s[42:43], 0, v[0:1]
	v_or_b32_e32 v0, 0x1800, v64
	s_cselect_b64 s[2:3], -1, 0
	v_lshl_add_u64 v[66:67], s[40:41], 0, v[64:65]
	v_lshl_add_u64 v[68:69], s[42:43], 0, v[64:65]
	v_lshl_add_u64 v[78:79], s[40:41], 0, v[0:1]
	v_lshl_add_u64 v[80:81], s[42:43], 0, v[0:1]
	v_or_b32_e32 v64, 0x1c00, v64
	v_and_b32_e32 v0, 63, v160
	v_lshl_add_u64 v[82:83], s[40:41], 0, v[64:65]
	v_lshl_add_u64 v[84:85], s[42:43], 0, v[64:65]
	v_lshlrev_b32_e32 v64, 4, v0
	v_cndmask_b32_e64 v0, 0, 1, s[2:3]
	s_ashr_i32 s4, s4, 3
	v_cmp_ne_u32_e64 s[2:3], 1, v0
	v_and_b32_e32 v0, 64, v161
	v_cmp_eq_u32_e64 s[0:1], 0, v160
	s_and_b32 s10, s4, -8
	s_movk_i32 s11, 0x1000
	v_lshl_add_u64 v[86:87], s[44:45], 0, v[64:65]
	s_movk_i32 s12, 0x207
	v_add_u32_e32 v98, 64, v0
	v_xor_b32_e32 v99, 32, v161
	v_xor_b32_e32 v100, 16, v161
	v_xor_b32_e32 v101, 8, v161
	v_xor_b32_e32 v102, 4, v161
	v_xor_b32_e32 v103, 2, v161
	v_xor_b32_e32 v104, 1, v161
	v_mov_b32_e32 v105, 0x3727c5ac
	s_mov_b32 s13, 0x800000
	s_mov_b32 s14, 0x8000
	s_mov_b32 s15, 0x9000
	global_load_dwordx4 v[112:115], v[66:67], off
	global_load_dwordx4 v[116:119], v[66:67], off offset:1024
	global_load_dwordx4 v[120:123], v[66:67], off offset:2048
	global_load_dwordx4 v[124:127], v[66:67], off offset:3072
	global_load_dwordx4 v[128:131], v[70:71], off
	global_load_dwordx4 v[132:135], v[70:71], off offset:1024
	global_load_dwordx4 v[136:139], v[70:71], off offset:2048
	global_load_dwordx4 v[140:143], v[70:71], off offset:3072
	global_load_dwordx4 v[144:147], v[68:69], off
	global_load_dwordx4 v[148:151], v[68:69], off offset:1024
	global_load_dwordx4 v[152:155], v[68:69], off offset:2048
	global_load_dwordx4 v[156:159], v[68:69], off offset:3072
	global_load_dwordx4 v[160:163], v[72:73], off
	global_load_dwordx4 v[164:167], v[72:73], off offset:1024
	global_load_dwordx4 v[168:171], v[72:73], off offset:2048
	global_load_dwordx4 v[172:175], v[72:73], off offset:3072
	s_branch .LBB0_660

; DI void ln_finish(const Params& p, float* __restrict__ pr, const float4 (&v)[8], int lane) {
;   float s = 0.f;
; #pragma unroll
;   for (int i = 0; i < 8; ++i) s += v[i].x + v[i].y + v[i].z + v[i].w;
; #pragma unroll
;   for (int o = 32; o >= 1; o >>= 1) s += __shfl_xor(s, o);
;   const float mu = s * (1.f / 2048.f);
;   float q = 0.f;
; #pragma unroll
;   for (int i = 0; i < 8; ++i) {
;     const float a = v[i].x - mu, b = v[i].y - mu, c = v[i].z - mu, d = v[i].w - mu;
;     q += a * a + b * b + c * c + d * d;
;   }
; #pragma unroll
;   for (int o = 32; o >= 1; o >>= 1) q += __shfl_xor(q, o);
;   const float rstd = rsqrtf(q * (1.f / 2048.f) + EPSV);
; __device__ void phaseD_handoff(const Params& p, unsigned char* smem) {
;     ...
;     const int row0 = panel * 256 + chunk * 64 + w * 8;
; #pragma unroll 1
;     for (int k = 0; k < 4; ++k) {
;       float* pa = p.out + O_Y + (size_t)(row0 + k) * 2048;
;       float* pb = p.out + O_Y + (size_t)(row0 + 4 + k) * 2048;
;       float4 va[8], vb[8];
; #pragma unroll
;       for (int i = 0; i < 8; ++i) va[i] = *reinterpret_cast<const float4*>(pa + (i * 64 + lane) * 4);
; #pragma unroll
;       for (int i = 0; i < 8; ++i) vb[i] = *reinterpret_cast<const float4*>(pb + (i * 64 + lane) * 4);
;       ln_finish(p, pa, va, lane);
;       ln_finish(p, pb, vb, lane);
;     }
.LBB0_670:
	s_lshl_b32 s4, s4, 8
	s_lshl_b32 s5, s6, 6
	s_and_b32 s5, s5, 0xc0
	s_add_i32 s4, s10, s4
	s_add_i32 s4, s4, s5
	s_ashr_i32 s5, s4, 31
	s_lshl_b64 s[4:5], s[4:5], 13
	v_lshl_add_u64 v[100:101], v[86:87], 0, s[4:5]
	s_barrier
	s_mov_b32 s24, 0x0
	s_mov_b32 s25, 0
	v_lshl_add_u64 v[88:89], v[100:101], 0, s[24:25]
	s_mov_b32 s24, 0x1000
	v_lshl_add_u64 v[90:91], v[100:101], 0, s[24:25]
	global_load_dwordx4 v[0:3], v[88:89], off
	global_load_dwordx4 v[4:7], v[88:89], off offset:1024
	global_load_dwordx4 v[8:11], v[88:89], off offset:2048
	global_load_dwordx4 v[12:15], v[88:89], off offset:3072
	global_load_dwordx4 v[16:19], v[90:91], off
	global_load_dwordx4 v[20:23], v[90:91], off offset:1024
	global_load_dwordx4 v[24:27], v[90:91], off offset:2048
	global_load_dwordx4 v[28:31], v[90:91], off offset:3072
	s_mov_b32 s24, 0x2000
	s_mov_b32 s25, 0
	v_lshl_add_u64 v[92:93], v[100:101], 0, s[24:25]
	s_mov_b32 s24, 0x3000
	v_lshl_add_u64 v[94:95], v[100:101], 0, s[24:25]
	global_load_dwordx4 v[32:35], v[92:93], off
	global_load_dwordx4 v[36:39], v[92:93], off offset:1024
	global_load_dwordx4 v[40:43], v[92:93], off offset:2048
	global_load_dwordx4 v[44:47], v[92:93], off offset:3072
	global_load_dwordx4 v[48:51], v[94:95], off
	global_load_dwordx4 v[52:55], v[94:95], off offset:1024
	global_load_dwordx4 v[56:59], v[94:95], off offset:2048
	global_load_dwordx4 v[60:63], v[94:95], off offset:3072
	s_mov_b32 s24, 0x4000
	s_mov_b32 s25, 0
	v_lshl_add_u64 v[96:97], v[100:101], 0, s[24:25]
	s_mov_b32 s24, 0x5000
	v_lshl_add_u64 v[98:99], v[100:101], 0, s[24:25]
	global_load_dwordx4 v[176:179], v[96:97], off
	global_load_dwordx4 v[180:183], v[96:97], off offset:1024
	global_load_dwordx4 v[184:187], v[96:97], off offset:2048
	global_load_dwordx4 v[188:191], v[96:97], off offset:3072
	global_load_dwordx4 v[192:195], v[98:99], off
	global_load_dwordx4 v[196:199], v[98:99], off offset:1024
	global_load_dwordx4 v[200:203], v[98:99], off offset:2048
	global_load_dwordx4 v[204:207], v[98:99], off offset:3072
	s_waitcnt vmcnt(16)
	v_add_f32_e32 v208, v0, v4
	v_add_f32_e32 v209, v1, v5
	v_add_f32_e32 v210, v2, v6
	v_add_f32_e32 v211, v3, v7
	v_add_f32_e32 v208, v8, v208
	v_add_f32_e32 v209, v9, v209
	v_add_f32_e32 v210, v10, v210
	v_add_f32_e32 v211, v11, v211
	v_add_f32_e32 v208, v12, v208
	v_add_f32_e32 v209, v13, v209
	v_add_f32_e32 v210, v14, v210
	v_add_f32_e32 v211, v15, v211
	v_add_f32_e32 v208, v16, v208
	v_add_f32_e32 v209, v17, v209
	v_add_f32_e32 v210, v18, v210
	v_add_f32_e32 v211, v19, v211
	v_add_f32_e32 v208, v20, v208
	v_add_f32_e32 v209, v21, v209
	v_add_f32_e32 v210, v22, v210
	v_add_f32_e32 v211, v23, v211
	v_add_f32_e32 v208, v24, v208
	v_add_f32_e32 v209, v25, v209
	v_add_f32_e32 v210, v26, v210
	v_add_f32_e32 v211, v27, v211
	v_add_f32_e32 v208, v28, v208
	v_add_f32_e32 v209, v29, v209
	v_add_f32_e32 v210, v30, v210
	v_add_f32_e32 v211, v31, v211
	v_add_f32_e32 v208, v208, v209
	v_add_f32_e32 v210, v210, v211
	v_add_f32_e32 v208, v208, v210
	s_nop 1
	v_add_f32_dpp v208, v208, v208 quad_perm:[1,0,3,2] row_mask:0xf bank_mask:0xf
	s_nop 1
	v_add_f32_dpp v208, v208, v208 quad_perm:[2,3,0,1] row_mask:0xf bank_mask:0xf
	s_nop 1
	v_add_f32_dpp v208, v208, v208 row_half_mirror row_mask:0xf bank_mask:0xf
	s_nop 1
	v_add_f32_dpp v208, v208, v208 row_mirror row_mask:0xf bank_mask:0xf
	s_nop 1
	v_readlane_b32 s16, v208, 0
	v_readlane_b32 s17, v208, 16
	v_readlane_b32 s18, v208, 32
	v_readlane_b32 s19, v208, 48
	s_nop 1
	v_mov_b32_e32 v208, s16
	v_add_f32_e32 v208, s17, v208
	v_add_f32_e32 v208, s18, v208
	v_add_f32_e32 v208, s19, v208
	v_mul_f32_e32 v212, 0x3a000000, v208
	v_sub_f32_e32 v0, v0, v212
	v_sub_f32_e32 v1, v1, v212
	v_sub_f32_e32 v2, v2, v212
	v_sub_f32_e32 v3, v3, v212
	v_sub_f32_e32 v4, v4, v212
	v_sub_f32_e32 v5, v5, v212
	v_sub_f32_e32 v6, v6, v212
	v_sub_f32_e32 v7, v7, v212
	v_sub_f32_e32 v8, v8, v212
	v_sub_f32_e32 v9, v9, v212
	v_sub_f32_e32 v10, v10, v212
	v_sub_f32_e32 v11, v11, v212
	v_sub_f32_e32 v12, v12, v212
	v_sub_f32_e32 v13, v13, v212
	v_sub_f32_e32 v14, v14, v212
	v_sub_f32_e32 v15, v15, v212
	v_sub_f32_e32 v16, v16, v212
	v_sub_f32_e32 v17, v17, v212
	v_sub_f32_e32 v18, v18, v212
	v_sub_f32_e32 v19, v19, v212
	v_sub_f32_e32 v20, v20, v212
	v_sub_f32_e32 v21, v21, v212
	v_sub_f32_e32 v22, v22, v212
	v_sub_f32_e32 v23, v23, v212
	v_sub_f32_e32 v24, v24, v212
	v_sub_f32_e32 v25, v25, v212
	v_sub_f32_e32 v26, v26, v212
	v_sub_f32_e32 v27, v27, v212
	v_sub_f32_e32 v28, v28, v212
	v_sub_f32_e32 v29, v29, v212
	v_sub_f32_e32 v30, v30, v212
	v_sub_f32_e32 v31, v31, v212
	v_mul_f32_e32 v208, v0, v0
	v_mul_f32_e32 v209, v1, v1
	v_mul_f32_e32 v210, v2, v2
	v_mul_f32_e32 v211, v3, v3
	v_fmac_f32_e32 v208, v4, v4
	v_fmac_f32_e32 v209, v5, v5
	v_fmac_f32_e32 v210, v6, v6
	v_fmac_f32_e32 v211, v7, v7
	v_fmac_f32_e32 v208, v8, v8
	v_fmac_f32_e32 v209, v9, v9
	v_fmac_f32_e32 v210, v10, v10
	v_fmac_f32_e32 v211, v11, v11
	v_fmac_f32_e32 v208, v12, v12
	v_fmac_f32_e32 v209, v13, v13
	v_fmac_f32_e32 v210, v14, v14
	v_fmac_f32_e32 v211, v15, v15
	v_fmac_f32_e32 v208, v16, v16
	v_fmac_f32_e32 v209, v17, v17
	v_fmac_f32_e32 v210, v18, v18
	v_fmac_f32_e32 v211, v19, v19
	v_fmac_f32_e32 v208, v20, v20
	v_fmac_f32_e32 v209, v21, v21
	v_fmac_f32_e32 v210, v22, v22
	v_fmac_f32_e32 v211, v23, v23
	v_fmac_f32_e32 v208, v24, v24
	v_fmac_f32_e32 v209, v25, v25
	v_fmac_f32_e32 v210, v26, v26
	v_fmac_f32_e32 v211, v27, v27
	v_fmac_f32_e32 v208, v28, v28
	v_fmac_f32_e32 v209, v29, v29
	v_fmac_f32_e32 v210, v30, v30
	v_fmac_f32_e32 v211, v31, v31
	v_add_f32_e32 v208, v208, v209
	v_add_f32_e32 v210, v210, v211
	v_add_f32_e32 v208, v208, v210
; DI void ln_finish(const Params& p, float* __restrict__ pr, const float4 (&v)[8], int lane) {
;   float s = 0.f;
; #pragma unroll
;   for (int i = 0; i < 8; ++i) s += v[i].x + v[i].y + v[i].z + v[i].w;
; #pragma unroll
;   for (int o = 32; o >= 1; o >>= 1) s += __shfl_xor(s, o);
;   const float mu = s * (1.f / 2048.f);
;   float q = 0.f;
; #pragma unroll
;   for (int i = 0; i < 8; ++i) {
;     const float a = v[i].x - mu, b = v[i].y - mu, c = v[i].z - mu, d = v[i].w - mu;
;     q += a * a + b * b + c * c + d * d;
;   }
; #pragma unroll
;   for (int o = 32; o >= 1; o >>= 1) q += __shfl_xor(q, o);
;   const float rstd = rsqrtf(q * (1.f / 2048.f) + EPSV);
; #pragma unroll
;   for (int i = 0; i < 8; ++i) {
;     const int c0 = (i * 64 + lane) * 4;
;     const float4 g = *reinterpret_cast<const float4*>(p.ln_g + c0);
;     const float4 bb = *reinterpret_cast<const float4*>(p.ln_b + c0);
;     float4 o;
;     o.x = (v[i].x - mu) * rstd * g.x + bb.x;
;     o.y = (v[i].y - mu) * rstd * g.y + bb.y;
;     o.z = (v[i].z - mu) * rstd * g.z + bb.z;
;     o.w = (v[i].w - mu) * rstd * g.w + bb.w;
;     *reinterpret_cast<float4*>(pr + c0) = o;
; __device__ void phaseD_handoff(const Params& p, unsigned char* smem) {
;     ...
;     const int row0 = panel * 256 + chunk * 64 + w * 8;
; #pragma unroll 1
;     for (int k = 0; k < 4; ++k) {
;       float* pa = p.out + O_Y + (size_t)(row0 + k) * 2048;
;       float* pb = p.out + O_Y + (size_t)(row0 + 4 + k) * 2048;
;       float4 va[8], vb[8];
; #pragma unroll
;       for (int i = 0; i < 8; ++i) va[i] = *reinterpret_cast<const float4*>(pa + (i * 64 + lane) * 4);
; #pragma unroll
;       for (int i = 0; i < 8; ++i) vb[i] = *reinterpret_cast<const float4*>(pb + (i * 64 + lane) * 4);
;       ln_finish(p, pa, va, lane);
;       ln_finish(p, pb, vb, lane);
;     }
	s_nop 1
	v_add_f32_dpp v208, v208, v208 quad_perm:[1,0,3,2] row_mask:0xf bank_mask:0xf
	s_nop 1
	v_add_f32_dpp v208, v208, v208 quad_perm:[2,3,0,1] row_mask:0xf bank_mask:0xf
	s_nop 1
	v_add_f32_dpp v208, v208, v208 row_half_mirror row_mask:0xf bank_mask:0xf
	s_nop 1
	v_add_f32_dpp v208, v208, v208 row_mirror row_mask:0xf bank_mask:0xf
	s_nop 1
	v_readlane_b32 s16, v208, 0
	v_readlane_b32 s17, v208, 16
	v_readlane_b32 s18, v208, 32
	v_readlane_b32 s19, v208, 48
	s_nop 1
	v_mov_b32_e32 v208, s16
	v_add_f32_e32 v208, s17, v208
	v_add_f32_e32 v208, s18, v208
	v_add_f32_e32 v208, s19, v208
	v_mov_b32_e32 v213, 0x3727c5ac
	v_fmac_f32_e32 v213, 0x3a000000, v208
	v_rsq_f32_e32 v213, v213
	s_nop 0
	v_mul_f32_e32 v0, v0, v213
	v_mul_f32_e32 v1, v1, v213
	v_mul_f32_e32 v2, v2, v213
	v_mul_f32_e32 v3, v3, v213
	v_mul_f32_e32 v4, v4, v213
	v_mul_f32_e32 v5, v5, v213
	v_mul_f32_e32 v6, v6, v213
	v_mul_f32_e32 v7, v7, v213
	v_mul_f32_e32 v8, v8, v213
	v_mul_f32_e32 v9, v9, v213
	v_mul_f32_e32 v10, v10, v213
	v_mul_f32_e32 v11, v11, v213
	v_mul_f32_e32 v12, v12, v213
	v_mul_f32_e32 v13, v13, v213
	v_mul_f32_e32 v14, v14, v213
	v_mul_f32_e32 v15, v15, v213
	v_mul_f32_e32 v16, v16, v213
	v_mul_f32_e32 v17, v17, v213
	v_mul_f32_e32 v18, v18, v213
	v_mul_f32_e32 v19, v19, v213
	v_mul_f32_e32 v20, v20, v213
	v_mul_f32_e32 v21, v21, v213
	v_mul_f32_e32 v22, v22, v213
	v_mul_f32_e32 v23, v23, v213
	v_mul_f32_e32 v24, v24, v213
	v_mul_f32_e32 v25, v25, v213
	v_mul_f32_e32 v26, v26, v213
	v_mul_f32_e32 v27, v27, v213
	v_mul_f32_e32 v28, v28, v213
	v_mul_f32_e32 v29, v29, v213
	v_mul_f32_e32 v30, v30, v213
	v_mul_f32_e32 v31, v31, v213
	v_fma_f32 v0, v0, v112, v144
	v_fma_f32 v1, v1, v113, v145
	v_fma_f32 v2, v2, v114, v146
	v_fma_f32 v3, v3, v115, v147
	v_fma_f32 v4, v4, v116, v148
	v_fma_f32 v5, v5, v117, v149
	v_fma_f32 v6, v6, v118, v150
	v_fma_f32 v7, v7, v119, v151
	v_fma_f32 v8, v8, v120, v152
	v_fma_f32 v9, v9, v121, v153
	v_fma_f32 v10, v10, v122, v154
	v_fma_f32 v11, v11, v123, v155
	v_fma_f32 v12, v12, v124, v156
	v_fma_f32 v13, v13, v125, v157
	v_fma_f32 v14, v14, v126, v158
	v_fma_f32 v15, v15, v127, v159
	v_fma_f32 v16, v16, v128, v160
	v_fma_f32 v17, v17, v129, v161
	v_fma_f32 v18, v18, v130, v162
	v_fma_f32 v19, v19, v131, v163
	v_fma_f32 v20, v20, v132, v164
	v_fma_f32 v21, v21, v133, v165
	v_fma_f32 v22, v22, v134, v166
	v_fma_f32 v23, v23, v135, v167
	v_fma_f32 v24, v24, v136, v168
	v_fma_f32 v25, v25, v137, v169
	v_fma_f32 v26, v26, v138, v170
	v_fma_f32 v27, v27, v139, v171
	v_fma_f32 v28, v28, v140, v172
	v_fma_f32 v29, v29, v141, v173
	v_fma_f32 v30, v30, v142, v174
	v_fma_f32 v31, v31, v143, v175
	global_store_dwordx4 v[88:89], v[0:3], off
	global_store_dwordx4 v[88:89], v[4:7], off offset:1024
	global_store_dwordx4 v[88:89], v[8:11], off offset:2048
	global_store_dwordx4 v[88:89], v[12:15], off offset:3072
	global_store_dwordx4 v[90:91], v[16:19], off
	global_store_dwordx4 v[90:91], v[20:23], off offset:1024
	global_store_dwordx4 v[90:91], v[24:27], off offset:2048
	global_store_dwordx4 v[90:91], v[28:31], off offset:3072
	s_mov_b32 s24, 0x6000
	s_mov_b32 s25, 0
	v_lshl_add_u64 v[88:89], v[100:101], 0, s[24:25]
	s_mov_b32 s24, 0x7000
	v_lshl_add_u64 v[90:91], v[100:101], 0, s[24:25]
	global_load_dwordx4 v[0:3], v[88:89], off
	global_load_dwordx4 v[4:7], v[88:89], off offset:1024
	global_load_dwordx4 v[8:11], v[88:89], off offset:2048
	global_load_dwordx4 v[12:15], v[88:89], off offset:3072
	global_load_dwordx4 v[16:19], v[90:91], off
	global_load_dwordx4 v[20:23], v[90:91], off offset:1024
	global_load_dwordx4 v[24:27], v[90:91], off offset:2048
	global_load_dwordx4 v[28:31], v[90:91], off offset:3072
	s_waitcnt vmcnt(24)
	v_add_f32_e32 v208, v32, v36
	v_add_f32_e32 v209, v33, v37
	v_add_f32_e32 v210, v34, v38
	v_add_f32_e32 v211, v35, v39
	v_add_f32_e32 v208, v40, v208
	v_add_f32_e32 v209, v41, v209
	v_add_f32_e32 v210, v42, v210
	v_add_f32_e32 v211, v43, v211
	v_add_f32_e32 v208, v44, v208
	v_add_f32_e32 v209, v45, v209
	v_add_f32_e32 v210, v46, v210
	v_add_f32_e32 v211, v47, v211
	v_add_f32_e32 v208, v48, v208
	v_add_f32_e32 v209, v49, v209
	v_add_f32_e32 v210, v50, v210
	v_add_f32_e32 v211, v51, v211
	v_add_f32_e32 v208, v52, v208
	v_add_f32_e32 v209, v53, v209
	v_add_f32_e32 v210, v54, v210
	v_add_f32_e32 v211, v55, v211
	v_add_f32_e32 v208, v56, v208
	v_add_f32_e32 v209, v57, v209
	v_add_f32_e32 v210, v58, v210
	v_add_f32_e32 v211, v59, v211
	v_add_f32_e32 v208, v60, v208
	v_add_f32_e32 v209, v61, v209
	v_add_f32_e32 v210, v62, v210
	v_add_f32_e32 v211, v63, v211
	v_add_f32_e32 v208, v208, v209
	v_add_f32_e32 v210, v210, v211
	v_add_f32_e32 v208, v208, v210
	s_nop 1
	v_add_f32_dpp v208, v208, v208 quad_perm:[1,0,3,2] row_mask:0xf bank_mask:0xf
	s_nop 1
	v_add_f32_dpp v208, v208, v208 quad_perm:[2,3,0,1] row_mask:0xf bank_mask:0xf
	s_nop 1
	v_add_f32_dpp v208, v208, v208 row_half_mirror row_mask:0xf bank_mask:0xf
	s_nop 1
	v_add_f32_dpp v208, v208, v208 row_mirror row_mask:0xf bank_mask:0xf
	s_nop 1
	v_readlane_b32 s16, v208, 0
	v_readlane_b32 s17, v208, 16
	v_readlane_b32 s18, v208, 32
	v_readlane_b32 s19, v208, 48
	s_nop 1
	v_mov_b32_e32 v208, s16
	v_add_f32_e32 v208, s17, v208
	v_add_f32_e32 v208, s18, v208
	v_add_f32_e32 v208, s19, v208
	v_mul_f32_e32 v212, 0x3a000000, v208
	v_sub_f32_e32 v32, v32, v212
	v_sub_f32_e32 v33, v33, v212
	v_sub_f32_e32 v34, v34, v212
	v_sub_f32_e32 v35, v35, v212
	v_sub_f32_e32 v36, v36, v212
	v_sub_f32_e32 v37, v37, v212
	v_sub_f32_e32 v38, v38, v212
	v_sub_f32_e32 v39, v39, v212
	v_sub_f32_e32 v40, v40, v212
	v_sub_f32_e32 v41, v41, v212
	v_sub_f32_e32 v42, v42, v212
	v_sub_f32_e32 v43, v43, v212
; DI void ln_finish(const Params& p, float* __restrict__ pr, const float4 (&v)[8], int lane) {
;   float s = 0.f;
; #pragma unroll
;   for (int i = 0; i < 8; ++i) s += v[i].x + v[i].y + v[i].z + v[i].w;
; #pragma unroll
;   for (int o = 32; o >= 1; o >>= 1) s += __shfl_xor(s, o);
;   const float mu = s * (1.f / 2048.f);
;   float q = 0.f;
; #pragma unroll
;   for (int i = 0; i < 8; ++i) {
;     const float a = v[i].x - mu, b = v[i].y - mu, c = v[i].z - mu, d = v[i].w - mu;
;     q += a * a + b * b + c * c + d * d;
;   }
; #pragma unroll
;   for (int o = 32; o >= 1; o >>= 1) q += __shfl_xor(q, o);
;   const float rstd = rsqrtf(q * (1.f / 2048.f) + EPSV);
; #pragma unroll
;   for (int i = 0; i < 8; ++i) {
;     const int c0 = (i * 64 + lane) * 4;
;     const float4 g = *reinterpret_cast<const float4*>(p.ln_g + c0);
;     const float4 bb = *reinterpret_cast<const float4*>(p.ln_b + c0);
;     float4 o;
;     o.x = (v[i].x - mu) * rstd * g.x + bb.x;
;     o.y = (v[i].y - mu) * rstd * g.y + bb.y;
;     o.z = (v[i].z - mu) * rstd * g.z + bb.z;
;     o.w = (v[i].w - mu) * rstd * g.w + bb.w;
;     *reinterpret_cast<float4*>(pr + c0) = o;
; __device__ void phaseD_handoff(const Params& p, unsigned char* smem) {
;     ...
;     const int row0 = panel * 256 + chunk * 64 + w * 8;
; #pragma unroll 1
;     for (int k = 0; k < 4; ++k) {
;       float* pa = p.out + O_Y + (size_t)(row0 + k) * 2048;
;       float* pb = p.out + O_Y + (size_t)(row0 + 4 + k) * 2048;
;       float4 va[8], vb[8];
; #pragma unroll
;       for (int i = 0; i < 8; ++i) va[i] = *reinterpret_cast<const float4*>(pa + (i * 64 + lane) * 4);
; #pragma unroll
;       for (int i = 0; i < 8; ++i) vb[i] = *reinterpret_cast<const float4*>(pb + (i * 64 + lane) * 4);
;       ln_finish(p, pa, va, lane);
;       ln_finish(p, pb, vb, lane);
;     }
	v_sub_f32_e32 v44, v44, v212
	v_sub_f32_e32 v45, v45, v212
	v_sub_f32_e32 v46, v46, v212
	v_sub_f32_e32 v47, v47, v212
	v_sub_f32_e32 v48, v48, v212
	v_sub_f32_e32 v49, v49, v212
	v_sub_f32_e32 v50, v50, v212
	v_sub_f32_e32 v51, v51, v212
	v_sub_f32_e32 v52, v52, v212
	v_sub_f32_e32 v53, v53, v212
	v_sub_f32_e32 v54, v54, v212
	v_sub_f32_e32 v55, v55, v212
	v_sub_f32_e32 v56, v56, v212
	v_sub_f32_e32 v57, v57, v212
	v_sub_f32_e32 v58, v58, v212
	v_sub_f32_e32 v59, v59, v212
	v_sub_f32_e32 v60, v60, v212
	v_sub_f32_e32 v61, v61, v212
	v_sub_f32_e32 v62, v62, v212
	v_sub_f32_e32 v63, v63, v212
	v_mul_f32_e32 v208, v32, v32
	v_mul_f32_e32 v209, v33, v33
	v_mul_f32_e32 v210, v34, v34
	v_mul_f32_e32 v211, v35, v35
	v_fmac_f32_e32 v208, v36, v36
	v_fmac_f32_e32 v209, v37, v37
	v_fmac_f32_e32 v210, v38, v38
	v_fmac_f32_e32 v211, v39, v39
	v_fmac_f32_e32 v208, v40, v40
	v_fmac_f32_e32 v209, v41, v41
	v_fmac_f32_e32 v210, v42, v42
	v_fmac_f32_e32 v211, v43, v43
	v_fmac_f32_e32 v208, v44, v44
	v_fmac_f32_e32 v209, v45, v45
	v_fmac_f32_e32 v210, v46, v46
	v_fmac_f32_e32 v211, v47, v47
	v_fmac_f32_e32 v208, v48, v48
	v_fmac_f32_e32 v209, v49, v49
	v_fmac_f32_e32 v210, v50, v50
	v_fmac_f32_e32 v211, v51, v51
	v_fmac_f32_e32 v208, v52, v52
	v_fmac_f32_e32 v209, v53, v53
	v_fmac_f32_e32 v210, v54, v54
	v_fmac_f32_e32 v211, v55, v55
	v_fmac_f32_e32 v208, v56, v56
	v_fmac_f32_e32 v209, v57, v57
	v_fmac_f32_e32 v210, v58, v58
	v_fmac_f32_e32 v211, v59, v59
	v_fmac_f32_e32 v208, v60, v60
	v_fmac_f32_e32 v209, v61, v61
	v_fmac_f32_e32 v210, v62, v62
	v_fmac_f32_e32 v211, v63, v63
	v_add_f32_e32 v208, v208, v209
	v_add_f32_e32 v210, v210, v211
	v_add_f32_e32 v208, v208, v210
	s_nop 1
	v_add_f32_dpp v208, v208, v208 quad_perm:[1,0,3,2] row_mask:0xf bank_mask:0xf
	s_nop 1
	v_add_f32_dpp v208, v208, v208 quad_perm:[2,3,0,1] row_mask:0xf bank_mask:0xf
	s_nop 1
	v_add_f32_dpp v208, v208, v208 row_half_mirror row_mask:0xf bank_mask:0xf
	s_nop 1
	v_add_f32_dpp v208, v208, v208 row_mirror row_mask:0xf bank_mask:0xf
	s_nop 1
	v_readlane_b32 s16, v208, 0
	v_readlane_b32 s17, v208, 16
	v_readlane_b32 s18, v208, 32
	v_readlane_b32 s19, v208, 48
	s_nop 1
	v_mov_b32_e32 v208, s16
	v_add_f32_e32 v208, s17, v208
	v_add_f32_e32 v208, s18, v208
	v_add_f32_e32 v208, s19, v208
	v_mov_b32_e32 v213, 0x3727c5ac
	v_fmac_f32_e32 v213, 0x3a000000, v208
	v_rsq_f32_e32 v213, v213
	s_nop 0
	v_mul_f32_e32 v32, v32, v213
	v_mul_f32_e32 v33, v33, v213
	v_mul_f32_e32 v34, v34, v213
	v_mul_f32_e32 v35, v35, v213
	v_mul_f32_e32 v36, v36, v213
	v_mul_f32_e32 v37, v37, v213
	v_mul_f32_e32 v38, v38, v213
	v_mul_f32_e32 v39, v39, v213
	v_mul_f32_e32 v40, v40, v213
	v_mul_f32_e32 v41, v41, v213
	v_mul_f32_e32 v42, v42, v213
	v_mul_f32_e32 v43, v43, v213
	v_mul_f32_e32 v44, v44, v213
	v_mul_f32_e32 v45, v45, v213
	v_mul_f32_e32 v46, v46, v213
	v_mul_f32_e32 v47, v47, v213
	v_mul_f32_e32 v48, v48, v213
	v_mul_f32_e32 v49, v49, v213
	v_mul_f32_e32 v50, v50, v213
	v_mul_f32_e32 v51, v51, v213
	v_mul_f32_e32 v52, v52, v213
	v_mul_f32_e32 v53, v53, v213
	v_mul_f32_e32 v54, v54, v213
	v_mul_f32_e32 v55, v55, v213
	v_mul_f32_e32 v56, v56, v213
	v_mul_f32_e32 v57, v57, v213
	v_mul_f32_e32 v58, v58, v213
	v_mul_f32_e32 v59, v59, v213
	v_mul_f32_e32 v60, v60, v213
	v_mul_f32_e32 v61, v61, v213
	v_mul_f32_e32 v62, v62, v213
	v_mul_f32_e32 v63, v63, v213
	v_fma_f32 v32, v32, v112, v144
	v_fma_f32 v33, v33, v113, v145
	v_fma_f32 v34, v34, v114, v146
	v_fma_f32 v35, v35, v115, v147
	v_fma_f32 v36, v36, v116, v148
	v_fma_f32 v37, v37, v117, v149
	v_fma_f32 v38, v38, v118, v150
	v_fma_f32 v39, v39, v119, v151
	v_fma_f32 v40, v40, v120, v152
	v_fma_f32 v41, v41, v121, v153
	v_fma_f32 v42, v42, v122, v154
	v_fma_f32 v43, v43, v123, v155
	v_fma_f32 v44, v44, v124, v156
	v_fma_f32 v45, v45, v125, v157
	v_fma_f32 v46, v46, v126, v158
	v_fma_f32 v47, v47, v127, v159
	v_fma_f32 v48, v48, v128, v160
	v_fma_f32 v49, v49, v129, v161
	v_fma_f32 v50, v50, v130, v162
	v_fma_f32 v51, v51, v131, v163
	v_fma_f32 v52, v52, v132, v164
	v_fma_f32 v53, v53, v133, v165
	v_fma_f32 v54, v54, v134, v166
	v_fma_f32 v55, v55, v135, v167
	v_fma_f32 v56, v56, v136, v168
	v_fma_f32 v57, v57, v137, v169
	v_fma_f32 v58, v58, v138, v170
	v_fma_f32 v59, v59, v139, v171
	v_fma_f32 v60, v60, v140, v172
	v_fma_f32 v61, v61, v141, v173
	v_fma_f32 v62, v62, v142, v174
	v_fma_f32 v63, v63, v143, v175
	global_store_dwordx4 v[92:93], v[32:35], off
	global_store_dwordx4 v[92:93], v[36:39], off offset:1024
	global_store_dwordx4 v[92:93], v[40:43], off offset:2048
	global_store_dwordx4 v[92:93], v[44:47], off offset:3072
	global_store_dwordx4 v[94:95], v[48:51], off
	global_store_dwordx4 v[94:95], v[52:55], off offset:1024
	global_store_dwordx4 v[94:95], v[56:59], off offset:2048
	global_store_dwordx4 v[94:95], v[60:63], off offset:3072
	s_mov_b32 s24, 0x8000
	s_mov_b32 s25, 0
	v_lshl_add_u64 v[92:93], v[100:101], 0, s[24:25]
	s_mov_b32 s24, 0x9000
	v_lshl_add_u64 v[94:95], v[100:101], 0, s[24:25]
	global_load_dwordx4 v[32:35], v[92:93], off
	global_load_dwordx4 v[36:39], v[92:93], off offset:1024
	global_load_dwordx4 v[40:43], v[92:93], off offset:2048
	global_load_dwordx4 v[44:47], v[92:93], off offset:3072
	global_load_dwordx4 v[48:51], v[94:95], off
	global_load_dwordx4 v[52:55], v[94:95], off offset:1024
	global_load_dwordx4 v[56:59], v[94:95], off offset:2048
	global_load_dwordx4 v[60:63], v[94:95], off offset:3072
	s_waitcnt vmcnt(32)
; DI void ln_finish(const Params& p, float* __restrict__ pr, const float4 (&v)[8], int lane) {
;   float s = 0.f;
; #pragma unroll
;   for (int i = 0; i < 8; ++i) s += v[i].x + v[i].y + v[i].z + v[i].w;
; #pragma unroll
;   for (int o = 32; o >= 1; o >>= 1) s += __shfl_xor(s, o);
;   const float mu = s * (1.f / 2048.f);
;   float q = 0.f;
; #pragma unroll
;   for (int i = 0; i < 8; ++i) {
;     const float a = v[i].x - mu, b = v[i].y - mu, c = v[i].z - mu, d = v[i].w - mu;
;     q += a * a + b * b + c * c + d * d;
;   }
; #pragma unroll
;   for (int o = 32; o >= 1; o >>= 1) q += __shfl_xor(q, o);
;   const float rstd = rsqrtf(q * (1.f / 2048.f) + EPSV);
; #pragma unroll
;   for (int i = 0; i < 8; ++i) {
;     const int c0 = (i * 64 + lane) * 4;
;     const float4 g = *reinterpret_cast<const float4*>(p.ln_g + c0);
;     const float4 bb = *reinterpret_cast<const float4*>(p.ln_b + c0);
;     float4 o;
;     o.x = (v[i].x - mu) * rstd * g.x + bb.x;
;     o.y = (v[i].y - mu) * rstd * g.y + bb.y;
;     o.z = (v[i].z - mu) * rstd * g.z + bb.z;
;     o.w = (v[i].w - mu) * rstd * g.w + bb.w;
; __device__ void phaseD_handoff(const Params& p, unsigned char* smem) {
;     ...
;     const int row0 = panel * 256 + chunk * 64 + w * 8;
; #pragma unroll 1
;     for (int k = 0; k < 4; ++k) {
;       float* pa = p.out + O_Y + (size_t)(row0 + k) * 2048;
;       float* pb = p.out + O_Y + (size_t)(row0 + 4 + k) * 2048;
;       float4 va[8], vb[8];
; #pragma unroll
;       for (int i = 0; i < 8; ++i) va[i] = *reinterpret_cast<const float4*>(pa + (i * 64 + lane) * 4);
; #pragma unroll
;       for (int i = 0; i < 8; ++i) vb[i] = *reinterpret_cast<const float4*>(pb + (i * 64 + lane) * 4);
;       ln_finish(p, pa, va, lane);
;       ln_finish(p, pb, vb, lane);
;     }
	v_add_f32_e32 v208, v176, v180
	v_add_f32_e32 v209, v177, v181
	v_add_f32_e32 v210, v178, v182
	v_add_f32_e32 v211, v179, v183
	v_add_f32_e32 v208, v184, v208
	v_add_f32_e32 v209, v185, v209
	v_add_f32_e32 v210, v186, v210
	v_add_f32_e32 v211, v187, v211
	v_add_f32_e32 v208, v188, v208
	v_add_f32_e32 v209, v189, v209
	v_add_f32_e32 v210, v190, v210
	v_add_f32_e32 v211, v191, v211
	v_add_f32_e32 v208, v192, v208
	v_add_f32_e32 v209, v193, v209
	v_add_f32_e32 v210, v194, v210
	v_add_f32_e32 v211, v195, v211
	v_add_f32_e32 v208, v196, v208
	v_add_f32_e32 v209, v197, v209
	v_add_f32_e32 v210, v198, v210
	v_add_f32_e32 v211, v199, v211
	v_add_f32_e32 v208, v200, v208
	v_add_f32_e32 v209, v201, v209
	v_add_f32_e32 v210, v202, v210
	v_add_f32_e32 v211, v203, v211
	v_add_f32_e32 v208, v204, v208
	v_add_f32_e32 v209, v205, v209
	v_add_f32_e32 v210, v206, v210
	v_add_f32_e32 v211, v207, v211
	v_add_f32_e32 v208, v208, v209
	v_add_f32_e32 v210, v210, v211
	v_add_f32_e32 v208, v208, v210
	s_nop 1
	v_add_f32_dpp v208, v208, v208 quad_perm:[1,0,3,2] row_mask:0xf bank_mask:0xf
	s_nop 1
	v_add_f32_dpp v208, v208, v208 quad_perm:[2,3,0,1] row_mask:0xf bank_mask:0xf
	s_nop 1
	v_add_f32_dpp v208, v208, v208 row_half_mirror row_mask:0xf bank_mask:0xf
	s_nop 1
	v_add_f32_dpp v208, v208, v208 row_mirror row_mask:0xf bank_mask:0xf
	s_nop 1
	v_readlane_b32 s16, v208, 0
	v_readlane_b32 s17, v208, 16
	v_readlane_b32 s18, v208, 32
	v_readlane_b32 s19, v208, 48
	s_nop 1
	v_mov_b32_e32 v208, s16
	v_add_f32_e32 v208, s17, v208
	v_add_f32_e32 v208, s18, v208
	v_add_f32_e32 v208, s19, v208
	v_mul_f32_e32 v212, 0x3a000000, v208
	v_sub_f32_e32 v176, v176, v212
	v_sub_f32_e32 v177, v177, v212
	v_sub_f32_e32 v178, v178, v212
	v_sub_f32_e32 v179, v179, v212
	v_sub_f32_e32 v180, v180, v212
	v_sub_f32_e32 v181, v181, v212
	v_sub_f32_e32 v182, v182, v212
	v_sub_f32_e32 v183, v183, v212
	v_sub_f32_e32 v184, v184, v212
	v_sub_f32_e32 v185, v185, v212
	v_sub_f32_e32 v186, v186, v212
	v_sub_f32_e32 v187, v187, v212
	v_sub_f32_e32 v188, v188, v212
	v_sub_f32_e32 v189, v189, v212
	v_sub_f32_e32 v190, v190, v212
	v_sub_f32_e32 v191, v191, v212
	v_sub_f32_e32 v192, v192, v212
	v_sub_f32_e32 v193, v193, v212
	v_sub_f32_e32 v194, v194, v212
	v_sub_f32_e32 v195, v195, v212
	v_sub_f32_e32 v196, v196, v212
	v_sub_f32_e32 v197, v197, v212
	v_sub_f32_e32 v198, v198, v212
	v_sub_f32_e32 v199, v199, v212
	v_sub_f32_e32 v200, v200, v212
	v_sub_f32_e32 v201, v201, v212
	v_sub_f32_e32 v202, v202, v212
	v_sub_f32_e32 v203, v203, v212
	v_sub_f32_e32 v204, v204, v212
	v_sub_f32_e32 v205, v205, v212
	v_sub_f32_e32 v206, v206, v212
	v_sub_f32_e32 v207, v207, v212
	v_mul_f32_e32 v208, v176, v176
	v_mul_f32_e32 v209, v177, v177
	v_mul_f32_e32 v210, v178, v178
	v_mul_f32_e32 v211, v179, v179
	v_fmac_f32_e32 v208, v180, v180
	v_fmac_f32_e32 v209, v181, v181
	v_fmac_f32_e32 v210, v182, v182
	v_fmac_f32_e32 v211, v183, v183
	v_fmac_f32_e32 v208, v184, v184
	v_fmac_f32_e32 v209, v185, v185
	v_fmac_f32_e32 v210, v186, v186
	v_fmac_f32_e32 v211, v187, v187
	v_fmac_f32_e32 v208, v188, v188
	v_fmac_f32_e32 v209, v189, v189
	v_fmac_f32_e32 v210, v190, v190
	v_fmac_f32_e32 v211, v191, v191
	v_fmac_f32_e32 v208, v192, v192
	v_fmac_f32_e32 v209, v193, v193
	v_fmac_f32_e32 v210, v194, v194
	v_fmac_f32_e32 v211, v195, v195
	v_fmac_f32_e32 v208, v196, v196
	v_fmac_f32_e32 v209, v197, v197
	v_fmac_f32_e32 v210, v198, v198
	v_fmac_f32_e32 v211, v199, v199
	v_fmac_f32_e32 v208, v200, v200
	v_fmac_f32_e32 v209, v201, v201
	v_fmac_f32_e32 v210, v202, v202
	v_fmac_f32_e32 v211, v203, v203
	v_fmac_f32_e32 v208, v204, v204
	v_fmac_f32_e32 v209, v205, v205
	v_fmac_f32_e32 v210, v206, v206
	v_fmac_f32_e32 v211, v207, v207
	v_add_f32_e32 v208, v208, v209
	v_add_f32_e32 v210, v210, v211
	v_add_f32_e32 v208, v208, v210
	s_nop 1
	v_add_f32_dpp v208, v208, v208 quad_perm:[1,0,3,2] row_mask:0xf bank_mask:0xf
	s_nop 1
	v_add_f32_dpp v208, v208, v208 quad_perm:[2,3,0,1] row_mask:0xf bank_mask:0xf
	s_nop 1
	v_add_f32_dpp v208, v208, v208 row_half_mirror row_mask:0xf bank_mask:0xf
	s_nop 1
	v_add_f32_dpp v208, v208, v208 row_mirror row_mask:0xf bank_mask:0xf
	s_nop 1
	v_readlane_b32 s16, v208, 0
	v_readlane_b32 s17, v208, 16
	v_readlane_b32 s18, v208, 32
	v_readlane_b32 s19, v208, 48
	s_nop 1
	v_mov_b32_e32 v208, s16
	v_add_f32_e32 v208, s17, v208
	v_add_f32_e32 v208, s18, v208
	v_add_f32_e32 v208, s19, v208
	v_mov_b32_e32 v213, 0x3727c5ac
	v_fmac_f32_e32 v213, 0x3a000000, v208
	v_rsq_f32_e32 v213, v213
	s_nop 0
	v_mul_f32_e32 v176, v176, v213
	v_mul_f32_e32 v177, v177, v213
	v_mul_f32_e32 v178, v178, v213
	v_mul_f32_e32 v179, v179, v213
	v_mul_f32_e32 v180, v180, v213
	v_mul_f32_e32 v181, v181, v213
	v_mul_f32_e32 v182, v182, v213
	v_mul_f32_e32 v183, v183, v213
	v_mul_f32_e32 v184, v184, v213
	v_mul_f32_e32 v185, v185, v213
	v_mul_f32_e32 v186, v186, v213
	v_mul_f32_e32 v187, v187, v213
	v_mul_f32_e32 v188, v188, v213
	v_mul_f32_e32 v189, v189, v213
	v_mul_f32_e32 v190, v190, v213
	v_mul_f32_e32 v191, v191, v213
	v_mul_f32_e32 v192, v192, v213
	v_mul_f32_e32 v193, v193, v213
	v_mul_f32_e32 v194, v194, v213
	v_mul_f32_e32 v195, v195, v213
	v_mul_f32_e32 v196, v196, v213
	v_mul_f32_e32 v197, v197, v213
	v_mul_f32_e32 v198, v198, v213
	v_mul_f32_e32 v199, v199, v213
	v_mul_f32_e32 v200, v200, v213
	v_mul_f32_e32 v201, v201, v213
	v_mul_f32_e32 v202, v202, v213
	v_mul_f32_e32 v203, v203, v213
	v_mul_f32_e32 v204, v204, v213
	v_mul_f32_e32 v205, v205, v213
	v_mul_f32_e32 v206, v206, v213
	v_mul_f32_e32 v207, v207, v213
	v_fma_f32 v176, v176, v112, v144
	v_fma_f32 v177, v177, v113, v145
	v_fma_f32 v178, v178, v114, v146
	v_fma_f32 v179, v179, v115, v147
; DI void ln_finish(const Params& p, float* __restrict__ pr, const float4 (&v)[8], int lane) {
;   float s = 0.f;
; #pragma unroll
;   for (int i = 0; i < 8; ++i) s += v[i].x + v[i].y + v[i].z + v[i].w;
; #pragma unroll
;   for (int o = 32; o >= 1; o >>= 1) s += __shfl_xor(s, o);
;   const float mu = s * (1.f / 2048.f);
;   float q = 0.f;
; #pragma unroll
;   for (int i = 0; i < 8; ++i) {
;     const float a = v[i].x - mu, b = v[i].y - mu, c = v[i].z - mu, d = v[i].w - mu;
;     q += a * a + b * b + c * c + d * d;
;   }
; #pragma unroll
;   for (int o = 32; o >= 1; o >>= 1) q += __shfl_xor(q, o);
;   const float rstd = rsqrtf(q * (1.f / 2048.f) + EPSV);
; #pragma unroll
;   for (int i = 0; i < 8; ++i) {
;     const int c0 = (i * 64 + lane) * 4;
;     const float4 g = *reinterpret_cast<const float4*>(p.ln_g + c0);
;     const float4 bb = *reinterpret_cast<const float4*>(p.ln_b + c0);
;     float4 o;
;     o.x = (v[i].x - mu) * rstd * g.x + bb.x;
;     o.y = (v[i].y - mu) * rstd * g.y + bb.y;
;     o.z = (v[i].z - mu) * rstd * g.z + bb.z;
;     o.w = (v[i].w - mu) * rstd * g.w + bb.w;
;     *reinterpret_cast<float4*>(pr + c0) = o;
; __device__ void phaseD_handoff(const Params& p, unsigned char* smem) {
;     ...
;     const int row0 = panel * 256 + chunk * 64 + w * 8;
; #pragma unroll 1
;     for (int k = 0; k < 4; ++k) {
;       float* pa = p.out + O_Y + (size_t)(row0 + k) * 2048;
;       float* pb = p.out + O_Y + (size_t)(row0 + 4 + k) * 2048;
;       float4 va[8], vb[8];
; #pragma unroll
;       for (int i = 0; i < 8; ++i) va[i] = *reinterpret_cast<const float4*>(pa + (i * 64 + lane) * 4);
; #pragma unroll
;       for (int i = 0; i < 8; ++i) vb[i] = *reinterpret_cast<const float4*>(pb + (i * 64 + lane) * 4);
;       ln_finish(p, pa, va, lane);
;       ln_finish(p, pb, vb, lane);
;     }
	v_fma_f32 v180, v180, v116, v148
	v_fma_f32 v181, v181, v117, v149
	v_fma_f32 v182, v182, v118, v150
	v_fma_f32 v183, v183, v119, v151
	v_fma_f32 v184, v184, v120, v152
	v_fma_f32 v185, v185, v121, v153
	v_fma_f32 v186, v186, v122, v154
	v_fma_f32 v187, v187, v123, v155
	v_fma_f32 v188, v188, v124, v156
	v_fma_f32 v189, v189, v125, v157
	v_fma_f32 v190, v190, v126, v158
	v_fma_f32 v191, v191, v127, v159
	v_fma_f32 v192, v192, v128, v160
	v_fma_f32 v193, v193, v129, v161
	v_fma_f32 v194, v194, v130, v162
	v_fma_f32 v195, v195, v131, v163
	v_fma_f32 v196, v196, v132, v164
	v_fma_f32 v197, v197, v133, v165
	v_fma_f32 v198, v198, v134, v166
	v_fma_f32 v199, v199, v135, v167
	v_fma_f32 v200, v200, v136, v168
	v_fma_f32 v201, v201, v137, v169
	v_fma_f32 v202, v202, v138, v170
	v_fma_f32 v203, v203, v139, v171
	v_fma_f32 v204, v204, v140, v172
	v_fma_f32 v205, v205, v141, v173
	v_fma_f32 v206, v206, v142, v174
	v_fma_f32 v207, v207, v143, v175
	global_store_dwordx4 v[96:97], v[176:179], off
	global_store_dwordx4 v[96:97], v[180:183], off offset:1024
	global_store_dwordx4 v[96:97], v[184:187], off offset:2048
	global_store_dwordx4 v[96:97], v[188:191], off offset:3072
	global_store_dwordx4 v[98:99], v[192:195], off
	global_store_dwordx4 v[98:99], v[196:199], off offset:1024
	global_store_dwordx4 v[98:99], v[200:203], off offset:2048
	global_store_dwordx4 v[98:99], v[204:207], off offset:3072
	s_mov_b32 s24, 0xa000
	s_mov_b32 s25, 0
	v_lshl_add_u64 v[96:97], v[100:101], 0, s[24:25]
	s_mov_b32 s24, 0xb000
	v_lshl_add_u64 v[98:99], v[100:101], 0, s[24:25]
	global_load_dwordx4 v[176:179], v[96:97], off
	global_load_dwordx4 v[180:183], v[96:97], off offset:1024
	global_load_dwordx4 v[184:187], v[96:97], off offset:2048
	global_load_dwordx4 v[188:191], v[96:97], off offset:3072
	global_load_dwordx4 v[192:195], v[98:99], off
	global_load_dwordx4 v[196:199], v[98:99], off offset:1024
	global_load_dwordx4 v[200:203], v[98:99], off offset:2048
	global_load_dwordx4 v[204:207], v[98:99], off offset:3072
	s_waitcnt vmcnt(32)
	v_add_f32_e32 v208, v0, v4
	v_add_f32_e32 v209, v1, v5
	v_add_f32_e32 v210, v2, v6
	v_add_f32_e32 v211, v3, v7
	v_add_f32_e32 v208, v8, v208
	v_add_f32_e32 v209, v9, v209
	v_add_f32_e32 v210, v10, v210
	v_add_f32_e32 v211, v11, v211
	v_add_f32_e32 v208, v12, v208
	v_add_f32_e32 v209, v13, v209
	v_add_f32_e32 v210, v14, v210
	v_add_f32_e32 v211, v15, v211
	v_add_f32_e32 v208, v16, v208
	v_add_f32_e32 v209, v17, v209
	v_add_f32_e32 v210, v18, v210
	v_add_f32_e32 v211, v19, v211
	v_add_f32_e32 v208, v20, v208
	v_add_f32_e32 v209, v21, v209
	v_add_f32_e32 v210, v22, v210
	v_add_f32_e32 v211, v23, v211
	v_add_f32_e32 v208, v24, v208
	v_add_f32_e32 v209, v25, v209
	v_add_f32_e32 v210, v26, v210
	v_add_f32_e32 v211, v27, v211
	v_add_f32_e32 v208, v28, v208
	v_add_f32_e32 v209, v29, v209
	v_add_f32_e32 v210, v30, v210
	v_add_f32_e32 v211, v31, v211
	v_add_f32_e32 v208, v208, v209
	v_add_f32_e32 v210, v210, v211
	v_add_f32_e32 v208, v208, v210
	s_nop 1
	v_add_f32_dpp v208, v208, v208 quad_perm:[1,0,3,2] row_mask:0xf bank_mask:0xf
	s_nop 1
	v_add_f32_dpp v208, v208, v208 quad_perm:[2,3,0,1] row_mask:0xf bank_mask:0xf
	s_nop 1
	v_add_f32_dpp v208, v208, v208 row_half_mirror row_mask:0xf bank_mask:0xf
	s_nop 1
	v_add_f32_dpp v208, v208, v208 row_mirror row_mask:0xf bank_mask:0xf
	s_nop 1
	v_readlane_b32 s16, v208, 0
	v_readlane_b32 s17, v208, 16
	v_readlane_b32 s18, v208, 32
	v_readlane_b32 s19, v208, 48
	s_nop 1
	v_mov_b32_e32 v208, s16
	v_add_f32_e32 v208, s17, v208
	v_add_f32_e32 v208, s18, v208
	v_add_f32_e32 v208, s19, v208
	v_mul_f32_e32 v212, 0x3a000000, v208
	v_sub_f32_e32 v0, v0, v212
	v_sub_f32_e32 v1, v1, v212
	v_sub_f32_e32 v2, v2, v212
	v_sub_f32_e32 v3, v3, v212
	v_sub_f32_e32 v4, v4, v212
	v_sub_f32_e32 v5, v5, v212
	v_sub_f32_e32 v6, v6, v212
	v_sub_f32_e32 v7, v7, v212
	v_sub_f32_e32 v8, v8, v212
	v_sub_f32_e32 v9, v9, v212
	v_sub_f32_e32 v10, v10, v212
	v_sub_f32_e32 v11, v11, v212
	v_sub_f32_e32 v12, v12, v212
	v_sub_f32_e32 v13, v13, v212
	v_sub_f32_e32 v14, v14, v212
	v_sub_f32_e32 v15, v15, v212
	v_sub_f32_e32 v16, v16, v212
	v_sub_f32_e32 v17, v17, v212
	v_sub_f32_e32 v18, v18, v212
	v_sub_f32_e32 v19, v19, v212
	v_sub_f32_e32 v20, v20, v212
	v_sub_f32_e32 v21, v21, v212
	v_sub_f32_e32 v22, v22, v212
	v_sub_f32_e32 v23, v23, v212
	v_sub_f32_e32 v24, v24, v212
	v_sub_f32_e32 v25, v25, v212
	v_sub_f32_e32 v26, v26, v212
	v_sub_f32_e32 v27, v27, v212
	v_sub_f32_e32 v28, v28, v212
	v_sub_f32_e32 v29, v29, v212
	v_sub_f32_e32 v30, v30, v212
	v_sub_f32_e32 v31, v31, v212
	v_mul_f32_e32 v208, v0, v0
	v_mul_f32_e32 v209, v1, v1
	v_mul_f32_e32 v210, v2, v2
	v_mul_f32_e32 v211, v3, v3
	v_fmac_f32_e32 v208, v4, v4
	v_fmac_f32_e32 v209, v5, v5
	v_fmac_f32_e32 v210, v6, v6
	v_fmac_f32_e32 v211, v7, v7
	v_fmac_f32_e32 v208, v8, v8
	v_fmac_f32_e32 v209, v9, v9
	v_fmac_f32_e32 v210, v10, v10
	v_fmac_f32_e32 v211, v11, v11
	v_fmac_f32_e32 v208, v12, v12
	v_fmac_f32_e32 v209, v13, v13
	v_fmac_f32_e32 v210, v14, v14
	v_fmac_f32_e32 v211, v15, v15
	v_fmac_f32_e32 v208, v16, v16
	v_fmac_f32_e32 v209, v17, v17
	v_fmac_f32_e32 v210, v18, v18
	v_fmac_f32_e32 v211, v19, v19
	v_fmac_f32_e32 v208, v20, v20
	v_fmac_f32_e32 v209, v21, v21
	v_fmac_f32_e32 v210, v22, v22
	v_fmac_f32_e32 v211, v23, v23
	v_fmac_f32_e32 v208, v24, v24
	v_fmac_f32_e32 v209, v25, v25
	v_fmac_f32_e32 v210, v26, v26
	v_fmac_f32_e32 v211, v27, v27
	v_fmac_f32_e32 v208, v28, v28
	v_fmac_f32_e32 v209, v29, v29
	v_fmac_f32_e32 v210, v30, v30
	v_fmac_f32_e32 v211, v31, v31
	v_add_f32_e32 v208, v208, v209
	v_add_f32_e32 v210, v210, v211
	v_add_f32_e32 v208, v208, v210
	s_nop 1
; DI void ln_finish(const Params& p, float* __restrict__ pr, const float4 (&v)[8], int lane) {
;   float s = 0.f;
; #pragma unroll
;   for (int i = 0; i < 8; ++i) s += v[i].x + v[i].y + v[i].z + v[i].w;
; #pragma unroll
;   for (int o = 32; o >= 1; o >>= 1) s += __shfl_xor(s, o);
;   const float mu = s * (1.f / 2048.f);
;   float q = 0.f;
; #pragma unroll
;   for (int i = 0; i < 8; ++i) {
;     const float a = v[i].x - mu, b = v[i].y - mu, c = v[i].z - mu, d = v[i].w - mu;
;     q += a * a + b * b + c * c + d * d;
;   }
; #pragma unroll
;   for (int o = 32; o >= 1; o >>= 1) q += __shfl_xor(q, o);
;   const float rstd = rsqrtf(q * (1.f / 2048.f) + EPSV);
; #pragma unroll
;   for (int i = 0; i < 8; ++i) {
;     const int c0 = (i * 64 + lane) * 4;
;     const float4 g = *reinterpret_cast<const float4*>(p.ln_g + c0);
;     const float4 bb = *reinterpret_cast<const float4*>(p.ln_b + c0);
;     float4 o;
;     o.x = (v[i].x - mu) * rstd * g.x + bb.x;
;     o.y = (v[i].y - mu) * rstd * g.y + bb.y;
;     o.z = (v[i].z - mu) * rstd * g.z + bb.z;
;     o.w = (v[i].w - mu) * rstd * g.w + bb.w;
;     *reinterpret_cast<float4*>(pr + c0) = o;
; __device__ void phaseD_handoff(const Params& p, unsigned char* smem) {
;     ...
;     const int row0 = panel * 256 + chunk * 64 + w * 8;
; #pragma unroll 1
;     for (int k = 0; k < 4; ++k) {
;       float* pa = p.out + O_Y + (size_t)(row0 + k) * 2048;
;       float* pb = p.out + O_Y + (size_t)(row0 + 4 + k) * 2048;
;       float4 va[8], vb[8];
; #pragma unroll
;       for (int i = 0; i < 8; ++i) va[i] = *reinterpret_cast<const float4*>(pa + (i * 64 + lane) * 4);
; #pragma unroll
;       for (int i = 0; i < 8; ++i) vb[i] = *reinterpret_cast<const float4*>(pb + (i * 64 + lane) * 4);
;       ln_finish(p, pa, va, lane);
;       ln_finish(p, pb, vb, lane);
;     }
	v_add_f32_dpp v208, v208, v208 quad_perm:[1,0,3,2] row_mask:0xf bank_mask:0xf
	s_nop 1
	v_add_f32_dpp v208, v208, v208 quad_perm:[2,3,0,1] row_mask:0xf bank_mask:0xf
	s_nop 1
	v_add_f32_dpp v208, v208, v208 row_half_mirror row_mask:0xf bank_mask:0xf
	s_nop 1
	v_add_f32_dpp v208, v208, v208 row_mirror row_mask:0xf bank_mask:0xf
	s_nop 1
	v_readlane_b32 s16, v208, 0
	v_readlane_b32 s17, v208, 16
	v_readlane_b32 s18, v208, 32
	v_readlane_b32 s19, v208, 48
	s_nop 1
	v_mov_b32_e32 v208, s16
	v_add_f32_e32 v208, s17, v208
	v_add_f32_e32 v208, s18, v208
	v_add_f32_e32 v208, s19, v208
	v_mov_b32_e32 v213, 0x3727c5ac
	v_fmac_f32_e32 v213, 0x3a000000, v208
	v_rsq_f32_e32 v213, v213
	s_nop 0
	v_mul_f32_e32 v0, v0, v213
	v_mul_f32_e32 v1, v1, v213
	v_mul_f32_e32 v2, v2, v213
	v_mul_f32_e32 v3, v3, v213
	v_mul_f32_e32 v4, v4, v213
	v_mul_f32_e32 v5, v5, v213
	v_mul_f32_e32 v6, v6, v213
	v_mul_f32_e32 v7, v7, v213
	v_mul_f32_e32 v8, v8, v213
	v_mul_f32_e32 v9, v9, v213
	v_mul_f32_e32 v10, v10, v213
	v_mul_f32_e32 v11, v11, v213
	v_mul_f32_e32 v12, v12, v213
	v_mul_f32_e32 v13, v13, v213
	v_mul_f32_e32 v14, v14, v213
	v_mul_f32_e32 v15, v15, v213
	v_mul_f32_e32 v16, v16, v213
	v_mul_f32_e32 v17, v17, v213
	v_mul_f32_e32 v18, v18, v213
	v_mul_f32_e32 v19, v19, v213
	v_mul_f32_e32 v20, v20, v213
	v_mul_f32_e32 v21, v21, v213
	v_mul_f32_e32 v22, v22, v213
	v_mul_f32_e32 v23, v23, v213
	v_mul_f32_e32 v24, v24, v213
	v_mul_f32_e32 v25, v25, v213
	v_mul_f32_e32 v26, v26, v213
	v_mul_f32_e32 v27, v27, v213
	v_mul_f32_e32 v28, v28, v213
	v_mul_f32_e32 v29, v29, v213
	v_mul_f32_e32 v30, v30, v213
	v_mul_f32_e32 v31, v31, v213
	v_fma_f32 v0, v0, v112, v144
	v_fma_f32 v1, v1, v113, v145
	v_fma_f32 v2, v2, v114, v146
	v_fma_f32 v3, v3, v115, v147
	v_fma_f32 v4, v4, v116, v148
	v_fma_f32 v5, v5, v117, v149
	v_fma_f32 v6, v6, v118, v150
	v_fma_f32 v7, v7, v119, v151
	v_fma_f32 v8, v8, v120, v152
	v_fma_f32 v9, v9, v121, v153
	v_fma_f32 v10, v10, v122, v154
	v_fma_f32 v11, v11, v123, v155
	v_fma_f32 v12, v12, v124, v156
	v_fma_f32 v13, v13, v125, v157
	v_fma_f32 v14, v14, v126, v158
	v_fma_f32 v15, v15, v127, v159
	v_fma_f32 v16, v16, v128, v160
	v_fma_f32 v17, v17, v129, v161
	v_fma_f32 v18, v18, v130, v162
	v_fma_f32 v19, v19, v131, v163
	v_fma_f32 v20, v20, v132, v164
	v_fma_f32 v21, v21, v133, v165
	v_fma_f32 v22, v22, v134, v166
	v_fma_f32 v23, v23, v135, v167
	v_fma_f32 v24, v24, v136, v168
	v_fma_f32 v25, v25, v137, v169
	v_fma_f32 v26, v26, v138, v170
	v_fma_f32 v27, v27, v139, v171
	v_fma_f32 v28, v28, v140, v172
	v_fma_f32 v29, v29, v141, v173
	v_fma_f32 v30, v30, v142, v174
	v_fma_f32 v31, v31, v143, v175
	global_store_dwordx4 v[88:89], v[0:3], off
	global_store_dwordx4 v[88:89], v[4:7], off offset:1024
	global_store_dwordx4 v[88:89], v[8:11], off offset:2048
	global_store_dwordx4 v[88:89], v[12:15], off offset:3072
	global_store_dwordx4 v[90:91], v[16:19], off
	global_store_dwordx4 v[90:91], v[20:23], off offset:1024
	global_store_dwordx4 v[90:91], v[24:27], off offset:2048
	global_store_dwordx4 v[90:91], v[28:31], off offset:3072
	s_mov_b32 s24, 0xc000
	s_mov_b32 s25, 0
	v_lshl_add_u64 v[88:89], v[100:101], 0, s[24:25]
	s_mov_b32 s24, 0xd000
	v_lshl_add_u64 v[90:91], v[100:101], 0, s[24:25]
	global_load_dwordx4 v[0:3], v[88:89], off
	global_load_dwordx4 v[4:7], v[88:89], off offset:1024
	global_load_dwordx4 v[8:11], v[88:89], off offset:2048
	global_load_dwordx4 v[12:15], v[88:89], off offset:3072
	global_load_dwordx4 v[16:19], v[90:91], off
	global_load_dwordx4 v[20:23], v[90:91], off offset:1024
	global_load_dwordx4 v[24:27], v[90:91], off offset:2048
	global_load_dwordx4 v[28:31], v[90:91], off offset:3072
	s_waitcnt vmcnt(32)
	v_add_f32_e32 v208, v32, v36
	v_add_f32_e32 v209, v33, v37
	v_add_f32_e32 v210, v34, v38
	v_add_f32_e32 v211, v35, v39
	v_add_f32_e32 v208, v40, v208
	v_add_f32_e32 v209, v41, v209
	v_add_f32_e32 v210, v42, v210
	v_add_f32_e32 v211, v43, v211
	v_add_f32_e32 v208, v44, v208
	v_add_f32_e32 v209, v45, v209
	v_add_f32_e32 v210, v46, v210
	v_add_f32_e32 v211, v47, v211
	v_add_f32_e32 v208, v48, v208
	v_add_f32_e32 v209, v49, v209
	v_add_f32_e32 v210, v50, v210
	v_add_f32_e32 v211, v51, v211
	v_add_f32_e32 v208, v52, v208
	v_add_f32_e32 v209, v53, v209
	v_add_f32_e32 v210, v54, v210
	v_add_f32_e32 v211, v55, v211
	v_add_f32_e32 v208, v56, v208
	v_add_f32_e32 v209, v57, v209
	v_add_f32_e32 v210, v58, v210
	v_add_f32_e32 v211, v59, v211
	v_add_f32_e32 v208, v60, v208
	v_add_f32_e32 v209, v61, v209
	v_add_f32_e32 v210, v62, v210
	v_add_f32_e32 v211, v63, v211
	v_add_f32_e32 v208, v208, v209
	v_add_f32_e32 v210, v210, v211
	v_add_f32_e32 v208, v208, v210
	s_nop 1
	v_add_f32_dpp v208, v208, v208 quad_perm:[1,0,3,2] row_mask:0xf bank_mask:0xf
	s_nop 1
	v_add_f32_dpp v208, v208, v208 quad_perm:[2,3,0,1] row_mask:0xf bank_mask:0xf
	s_nop 1
	v_add_f32_dpp v208, v208, v208 row_half_mirror row_mask:0xf bank_mask:0xf
	s_nop 1
	v_add_f32_dpp v208, v208, v208 row_mirror row_mask:0xf bank_mask:0xf
	s_nop 1
	v_readlane_b32 s16, v208, 0
	v_readlane_b32 s17, v208, 16
	v_readlane_b32 s18, v208, 32
	v_readlane_b32 s19, v208, 48
	s_nop 1
	v_mov_b32_e32 v208, s16
	v_add_f32_e32 v208, s17, v208
	v_add_f32_e32 v208, s18, v208
	v_add_f32_e32 v208, s19, v208
	v_mul_f32_e32 v212, 0x3a000000, v208
	v_sub_f32_e32 v32, v32, v212
	v_sub_f32_e32 v33, v33, v212
	v_sub_f32_e32 v34, v34, v212
	v_sub_f32_e32 v35, v35, v212
	v_sub_f32_e32 v36, v36, v212
	v_sub_f32_e32 v37, v37, v212
	v_sub_f32_e32 v38, v38, v212
	v_sub_f32_e32 v39, v39, v212
	v_sub_f32_e32 v40, v40, v212
	v_sub_f32_e32 v41, v41, v212
	v_sub_f32_e32 v42, v42, v212
	v_sub_f32_e32 v43, v43, v212
; DI void ln_finish(const Params& p, float* __restrict__ pr, const float4 (&v)[8], int lane) {
;     ...
;   const float mu = s * (1.f / 2048.f);
;   float q = 0.f;
; #pragma unroll
;   for (int i = 0; i < 8; ++i) {
;     const float a = v[i].x - mu, b = v[i].y - mu, c = v[i].z - mu, d = v[i].w - mu;
;     q += a * a + b * b + c * c + d * d;
;   }
; #pragma unroll
;   for (int o = 32; o >= 1; o >>= 1) q += __shfl_xor(q, o);
;   const float rstd = rsqrtf(q * (1.f / 2048.f) + EPSV);
; #pragma unroll
;   for (int i = 0; i < 8; ++i) {
;     const int c0 = (i * 64 + lane) * 4;
;     const float4 g = *reinterpret_cast<const float4*>(p.ln_g + c0);
;     const float4 bb = *reinterpret_cast<const float4*>(p.ln_b + c0);
;     float4 o;
;     o.x = (v[i].x - mu) * rstd * g.x + bb.x;
;     o.y = (v[i].y - mu) * rstd * g.y + bb.y;
;     o.z = (v[i].z - mu) * rstd * g.z + bb.z;
;     o.w = (v[i].w - mu) * rstd * g.w + bb.w;
;     *reinterpret_cast<float4*>(pr + c0) = o;
; __device__ void phaseD_handoff(const Params& p, unsigned char* smem) {
;     ...
;     for (int k = 0; k < 4; ++k) {
;       float* pa = p.out + O_Y + (size_t)(row0 + k) * 2048;
;       float* pb = p.out + O_Y + (size_t)(row0 + 4 + k) * 2048;
;       float4 va[8], vb[8];
; #pragma unroll
;       for (int i = 0; i < 8; ++i) va[i] = *reinterpret_cast<const float4*>(pa + (i * 64 + lane) * 4);
; #pragma unroll
;       for (int i = 0; i < 8; ++i) vb[i] = *reinterpret_cast<const float4*>(pb + (i * 64 + lane) * 4);
	v_sub_f32_e32 v44, v44, v212
	v_sub_f32_e32 v45, v45, v212
	v_sub_f32_e32 v46, v46, v212
	v_sub_f32_e32 v47, v47, v212
	v_sub_f32_e32 v48, v48, v212
	v_sub_f32_e32 v49, v49, v212
	v_sub_f32_e32 v50, v50, v212
	v_sub_f32_e32 v51, v51, v212
	v_sub_f32_e32 v52, v52, v212
	v_sub_f32_e32 v53, v53, v212
	v_sub_f32_e32 v54, v54, v212
	v_sub_f32_e32 v55, v55, v212
	v_sub_f32_e32 v56, v56, v212
	v_sub_f32_e32 v57, v57, v212
	v_sub_f32_e32 v58, v58, v212
	v_sub_f32_e32 v59, v59, v212
	v_sub_f32_e32 v60, v60, v212
	v_sub_f32_e32 v61, v61, v212
	v_sub_f32_e32 v62, v62, v212
	v_sub_f32_e32 v63, v63, v212
	v_mul_f32_e32 v208, v32, v32
	v_mul_f32_e32 v209, v33, v33
	v_mul_f32_e32 v210, v34, v34
	v_mul_f32_e32 v211, v35, v35
	v_fmac_f32_e32 v208, v36, v36
	v_fmac_f32_e32 v209, v37, v37
	v_fmac_f32_e32 v210, v38, v38
	v_fmac_f32_e32 v211, v39, v39
	v_fmac_f32_e32 v208, v40, v40
	v_fmac_f32_e32 v209, v41, v41
	v_fmac_f32_e32 v210, v42, v42
	v_fmac_f32_e32 v211, v43, v43
	v_fmac_f32_e32 v208, v44, v44
	v_fmac_f32_e32 v209, v45, v45
	v_fmac_f32_e32 v210, v46, v46
	v_fmac_f32_e32 v211, v47, v47
	v_fmac_f32_e32 v208, v48, v48
	v_fmac_f32_e32 v209, v49, v49
	v_fmac_f32_e32 v210, v50, v50
	v_fmac_f32_e32 v211, v51, v51
	v_fmac_f32_e32 v208, v52, v52
	v_fmac_f32_e32 v209, v53, v53
	v_fmac_f32_e32 v210, v54, v54
	v_fmac_f32_e32 v211, v55, v55
	v_fmac_f32_e32 v208, v56, v56
	v_fmac_f32_e32 v209, v57, v57
	v_fmac_f32_e32 v210, v58, v58
	v_fmac_f32_e32 v211, v59, v59
	v_fmac_f32_e32 v208, v60, v60
	v_fmac_f32_e32 v209, v61, v61
	v_fmac_f32_e32 v210, v62, v62
	v_fmac_f32_e32 v211, v63, v63
	v_add_f32_e32 v208, v208, v209
	v_add_f32_e32 v210, v210, v211
	v_add_f32_e32 v208, v208, v210
	s_nop 1
	v_add_f32_dpp v208, v208, v208 quad_perm:[1,0,3,2] row_mask:0xf bank_mask:0xf
	s_nop 1
	v_add_f32_dpp v208, v208, v208 quad_perm:[2,3,0,1] row_mask:0xf bank_mask:0xf
	s_nop 1
	v_add_f32_dpp v208, v208, v208 row_half_mirror row_mask:0xf bank_mask:0xf
	s_nop 1
	v_add_f32_dpp v208, v208, v208 row_mirror row_mask:0xf bank_mask:0xf
	s_nop 1
	v_readlane_b32 s16, v208, 0
	v_readlane_b32 s17, v208, 16
	v_readlane_b32 s18, v208, 32
	v_readlane_b32 s19, v208, 48
	s_nop 1
	v_mov_b32_e32 v208, s16
	v_add_f32_e32 v208, s17, v208
	v_add_f32_e32 v208, s18, v208
	v_add_f32_e32 v208, s19, v208
	v_mov_b32_e32 v213, 0x3727c5ac
	v_fmac_f32_e32 v213, 0x3a000000, v208
	v_rsq_f32_e32 v213, v213
	s_nop 0
	v_mul_f32_e32 v32, v32, v213
	v_mul_f32_e32 v33, v33, v213
	v_mul_f32_e32 v34, v34, v213
	v_mul_f32_e32 v35, v35, v213
	v_mul_f32_e32 v36, v36, v213
	v_mul_f32_e32 v37, v37, v213
	v_mul_f32_e32 v38, v38, v213
	v_mul_f32_e32 v39, v39, v213
	v_mul_f32_e32 v40, v40, v213
	v_mul_f32_e32 v41, v41, v213
	v_mul_f32_e32 v42, v42, v213
	v_mul_f32_e32 v43, v43, v213
	v_mul_f32_e32 v44, v44, v213
	v_mul_f32_e32 v45, v45, v213
	v_mul_f32_e32 v46, v46, v213
	v_mul_f32_e32 v47, v47, v213
	v_mul_f32_e32 v48, v48, v213
	v_mul_f32_e32 v49, v49, v213
	v_mul_f32_e32 v50, v50, v213
	v_mul_f32_e32 v51, v51, v213
	v_mul_f32_e32 v52, v52, v213
	v_mul_f32_e32 v53, v53, v213
	v_mul_f32_e32 v54, v54, v213
	v_mul_f32_e32 v55, v55, v213
	v_mul_f32_e32 v56, v56, v213
	v_mul_f32_e32 v57, v57, v213
	v_mul_f32_e32 v58, v58, v213
	v_mul_f32_e32 v59, v59, v213
	v_mul_f32_e32 v60, v60, v213
	v_mul_f32_e32 v61, v61, v213
	v_mul_f32_e32 v62, v62, v213
	v_mul_f32_e32 v63, v63, v213
	v_fma_f32 v32, v32, v112, v144
	v_fma_f32 v33, v33, v113, v145
	v_fma_f32 v34, v34, v114, v146
	v_fma_f32 v35, v35, v115, v147
	v_fma_f32 v36, v36, v116, v148
	v_fma_f32 v37, v37, v117, v149
	v_fma_f32 v38, v38, v118, v150
	v_fma_f32 v39, v39, v119, v151
	v_fma_f32 v40, v40, v120, v152
	v_fma_f32 v41, v41, v121, v153
	v_fma_f32 v42, v42, v122, v154
	v_fma_f32 v43, v43, v123, v155
	v_fma_f32 v44, v44, v124, v156
	v_fma_f32 v45, v45, v125, v157
	v_fma_f32 v46, v46, v126, v158
	v_fma_f32 v47, v47, v127, v159
	v_fma_f32 v48, v48, v128, v160
	v_fma_f32 v49, v49, v129, v161
	v_fma_f32 v50, v50, v130, v162
	v_fma_f32 v51, v51, v131, v163
	v_fma_f32 v52, v52, v132, v164
	v_fma_f32 v53, v53, v133, v165
	v_fma_f32 v54, v54, v134, v166
	v_fma_f32 v55, v55, v135, v167
	v_fma_f32 v56, v56, v136, v168
	v_fma_f32 v57, v57, v137, v169
	v_fma_f32 v58, v58, v138, v170
	v_fma_f32 v59, v59, v139, v171
	v_fma_f32 v60, v60, v140, v172
	v_fma_f32 v61, v61, v141, v173
	v_fma_f32 v62, v62, v142, v174
	v_fma_f32 v63, v63, v143, v175
	global_store_dwordx4 v[92:93], v[32:35], off
	global_store_dwordx4 v[92:93], v[36:39], off offset:1024
	global_store_dwordx4 v[92:93], v[40:43], off offset:2048
	global_store_dwordx4 v[92:93], v[44:47], off offset:3072
	global_store_dwordx4 v[94:95], v[48:51], off
	global_store_dwordx4 v[94:95], v[52:55], off offset:1024
	global_store_dwordx4 v[94:95], v[56:59], off offset:2048
	global_store_dwordx4 v[94:95], v[60:63], off offset:3072
	s_mov_b32 s24, 0xe000
	s_mov_b32 s25, 0
	v_lshl_add_u64 v[92:93], v[100:101], 0, s[24:25]
	s_mov_b32 s24, 0xf000
	v_lshl_add_u64 v[94:95], v[100:101], 0, s[24:25]
	global_load_dwordx4 v[32:35], v[92:93], off
	global_load_dwordx4 v[36:39], v[92:93], off offset:1024
	global_load_dwordx4 v[40:43], v[92:93], off offset:2048
	global_load_dwordx4 v[44:47], v[92:93], off offset:3072
	global_load_dwordx4 v[48:51], v[94:95], off
	global_load_dwordx4 v[52:55], v[94:95], off offset:1024
	global_load_dwordx4 v[56:59], v[94:95], off offset:2048
	global_load_dwordx4 v[60:63], v[94:95], off offset:3072
	s_waitcnt vmcnt(32)
; DI void ln_finish(const Params& p, float* __restrict__ pr, const float4 (&v)[8], int lane) {
;   float s = 0.f;
; #pragma unroll
;   for (int i = 0; i < 8; ++i) s += v[i].x + v[i].y + v[i].z + v[i].w;
; #pragma unroll
;   for (int o = 32; o >= 1; o >>= 1) s += __shfl_xor(s, o);
;   const float mu = s * (1.f / 2048.f);
;   float q = 0.f;
; #pragma unroll
;   for (int i = 0; i < 8; ++i) {
;     const float a = v[i].x - mu, b = v[i].y - mu, c = v[i].z - mu, d = v[i].w - mu;
;     q += a * a + b * b + c * c + d * d;
;   }
; #pragma unroll
;   for (int o = 32; o >= 1; o >>= 1) q += __shfl_xor(q, o);
;   const float rstd = rsqrtf(q * (1.f / 2048.f) + EPSV);
; #pragma unroll
;   for (int i = 0; i < 8; ++i) {
;     const int c0 = (i * 64 + lane) * 4;
;     const float4 g = *reinterpret_cast<const float4*>(p.ln_g + c0);
;     const float4 bb = *reinterpret_cast<const float4*>(p.ln_b + c0);
;     float4 o;
;     o.x = (v[i].x - mu) * rstd * g.x + bb.x;
;     o.y = (v[i].y - mu) * rstd * g.y + bb.y;
;     o.z = (v[i].z - mu) * rstd * g.z + bb.z;
;     o.w = (v[i].w - mu) * rstd * g.w + bb.w;
	v_add_f32_e32 v208, v176, v180
	v_add_f32_e32 v209, v177, v181
	v_add_f32_e32 v210, v178, v182
	v_add_f32_e32 v211, v179, v183
	v_add_f32_e32 v208, v184, v208
	v_add_f32_e32 v209, v185, v209
	v_add_f32_e32 v210, v186, v210
	v_add_f32_e32 v211, v187, v211
	v_add_f32_e32 v208, v188, v208
	v_add_f32_e32 v209, v189, v209
	v_add_f32_e32 v210, v190, v210
	v_add_f32_e32 v211, v191, v211
	v_add_f32_e32 v208, v192, v208
	v_add_f32_e32 v209, v193, v209
	v_add_f32_e32 v210, v194, v210
	v_add_f32_e32 v211, v195, v211
	v_add_f32_e32 v208, v196, v208
	v_add_f32_e32 v209, v197, v209
	v_add_f32_e32 v210, v198, v210
	v_add_f32_e32 v211, v199, v211
	v_add_f32_e32 v208, v200, v208
	v_add_f32_e32 v209, v201, v209
	v_add_f32_e32 v210, v202, v210
	v_add_f32_e32 v211, v203, v211
	v_add_f32_e32 v208, v204, v208
	v_add_f32_e32 v209, v205, v209
	v_add_f32_e32 v210, v206, v210
	v_add_f32_e32 v211, v207, v211
	v_add_f32_e32 v208, v208, v209
	v_add_f32_e32 v210, v210, v211
	v_add_f32_e32 v208, v208, v210
	s_nop 1
	v_add_f32_dpp v208, v208, v208 quad_perm:[1,0,3,2] row_mask:0xf bank_mask:0xf
	s_nop 1
	v_add_f32_dpp v208, v208, v208 quad_perm:[2,3,0,1] row_mask:0xf bank_mask:0xf
	s_nop 1
	v_add_f32_dpp v208, v208, v208 row_half_mirror row_mask:0xf bank_mask:0xf
	s_nop 1
	v_add_f32_dpp v208, v208, v208 row_mirror row_mask:0xf bank_mask:0xf
	s_nop 1
	v_readlane_b32 s16, v208, 0
	v_readlane_b32 s17, v208, 16
	v_readlane_b32 s18, v208, 32
	v_readlane_b32 s19, v208, 48
	s_nop 1
	v_mov_b32_e32 v208, s16
	v_add_f32_e32 v208, s17, v208
	v_add_f32_e32 v208, s18, v208
	v_add_f32_e32 v208, s19, v208
	v_mul_f32_e32 v212, 0x3a000000, v208
	v_sub_f32_e32 v176, v176, v212
	v_sub_f32_e32 v177, v177, v212
	v_sub_f32_e32 v178, v178, v212
	v_sub_f32_e32 v179, v179, v212
	v_sub_f32_e32 v180, v180, v212
	v_sub_f32_e32 v181, v181, v212
	v_sub_f32_e32 v182, v182, v212
	v_sub_f32_e32 v183, v183, v212
	v_sub_f32_e32 v184, v184, v212
	v_sub_f32_e32 v185, v185, v212
	v_sub_f32_e32 v186, v186, v212
	v_sub_f32_e32 v187, v187, v212
	v_sub_f32_e32 v188, v188, v212
	v_sub_f32_e32 v189, v189, v212
	v_sub_f32_e32 v190, v190, v212
	v_sub_f32_e32 v191, v191, v212
	v_sub_f32_e32 v192, v192, v212
	v_sub_f32_e32 v193, v193, v212
	v_sub_f32_e32 v194, v194, v212
	v_sub_f32_e32 v195, v195, v212
	v_sub_f32_e32 v196, v196, v212
	v_sub_f32_e32 v197, v197, v212
	v_sub_f32_e32 v198, v198, v212
	v_sub_f32_e32 v199, v199, v212
	v_sub_f32_e32 v200, v200, v212
	v_sub_f32_e32 v201, v201, v212
	v_sub_f32_e32 v202, v202, v212
	v_sub_f32_e32 v203, v203, v212
	v_sub_f32_e32 v204, v204, v212
	v_sub_f32_e32 v205, v205, v212
	v_sub_f32_e32 v206, v206, v212
	v_sub_f32_e32 v207, v207, v212
	v_mul_f32_e32 v208, v176, v176
	v_mul_f32_e32 v209, v177, v177
	v_mul_f32_e32 v210, v178, v178
	v_mul_f32_e32 v211, v179, v179
	v_fmac_f32_e32 v208, v180, v180
	v_fmac_f32_e32 v209, v181, v181
	v_fmac_f32_e32 v210, v182, v182
	v_fmac_f32_e32 v211, v183, v183
	v_fmac_f32_e32 v208, v184, v184
	v_fmac_f32_e32 v209, v185, v185
	v_fmac_f32_e32 v210, v186, v186
	v_fmac_f32_e32 v211, v187, v187
	v_fmac_f32_e32 v208, v188, v188
	v_fmac_f32_e32 v209, v189, v189
	v_fmac_f32_e32 v210, v190, v190
	v_fmac_f32_e32 v211, v191, v191
	v_fmac_f32_e32 v208, v192, v192
	v_fmac_f32_e32 v209, v193, v193
	v_fmac_f32_e32 v210, v194, v194
	v_fmac_f32_e32 v211, v195, v195
	v_fmac_f32_e32 v208, v196, v196
	v_fmac_f32_e32 v209, v197, v197
	v_fmac_f32_e32 v210, v198, v198
	v_fmac_f32_e32 v211, v199, v199
	v_fmac_f32_e32 v208, v200, v200
	v_fmac_f32_e32 v209, v201, v201
	v_fmac_f32_e32 v210, v202, v202
	v_fmac_f32_e32 v211, v203, v203
	v_fmac_f32_e32 v208, v204, v204
	v_fmac_f32_e32 v209, v205, v205
	v_fmac_f32_e32 v210, v206, v206
	v_fmac_f32_e32 v211, v207, v207
	v_add_f32_e32 v208, v208, v209
	v_add_f32_e32 v210, v210, v211
	v_add_f32_e32 v208, v208, v210
	s_nop 1
	v_add_f32_dpp v208, v208, v208 quad_perm:[1,0,3,2] row_mask:0xf bank_mask:0xf
	s_nop 1
	v_add_f32_dpp v208, v208, v208 quad_perm:[2,3,0,1] row_mask:0xf bank_mask:0xf
	s_nop 1
	v_add_f32_dpp v208, v208, v208 row_half_mirror row_mask:0xf bank_mask:0xf
	s_nop 1
	v_add_f32_dpp v208, v208, v208 row_mirror row_mask:0xf bank_mask:0xf
	s_nop 1
	v_readlane_b32 s16, v208, 0
	v_readlane_b32 s17, v208, 16
	v_readlane_b32 s18, v208, 32
	v_readlane_b32 s19, v208, 48
	s_nop 1
	v_mov_b32_e32 v208, s16
	v_add_f32_e32 v208, s17, v208
	v_add_f32_e32 v208, s18, v208
	v_add_f32_e32 v208, s19, v208
	v_mov_b32_e32 v213, 0x3727c5ac
	v_fmac_f32_e32 v213, 0x3a000000, v208
	v_rsq_f32_e32 v213, v213
	s_nop 0
	v_mul_f32_e32 v176, v176, v213
	v_mul_f32_e32 v177, v177, v213
	v_mul_f32_e32 v178, v178, v213
	v_mul_f32_e32 v179, v179, v213
	v_mul_f32_e32 v180, v180, v213
	v_mul_f32_e32 v181, v181, v213
	v_mul_f32_e32 v182, v182, v213
	v_mul_f32_e32 v183, v183, v213
	v_mul_f32_e32 v184, v184, v213
	v_mul_f32_e32 v185, v185, v213
	v_mul_f32_e32 v186, v186, v213
	v_mul_f32_e32 v187, v187, v213
	v_mul_f32_e32 v188, v188, v213
	v_mul_f32_e32 v189, v189, v213
	v_mul_f32_e32 v190, v190, v213
	v_mul_f32_e32 v191, v191, v213
	v_mul_f32_e32 v192, v192, v213
	v_mul_f32_e32 v193, v193, v213
	v_mul_f32_e32 v194, v194, v213
	v_mul_f32_e32 v195, v195, v213
	v_mul_f32_e32 v196, v196, v213
	v_mul_f32_e32 v197, v197, v213
	v_mul_f32_e32 v198, v198, v213
	v_mul_f32_e32 v199, v199, v213
	v_mul_f32_e32 v200, v200, v213
	v_mul_f32_e32 v201, v201, v213
	v_mul_f32_e32 v202, v202, v213
	v_mul_f32_e32 v203, v203, v213
	v_mul_f32_e32 v204, v204, v213
	v_mul_f32_e32 v205, v205, v213
	v_mul_f32_e32 v206, v206, v213
	v_mul_f32_e32 v207, v207, v213
	v_fma_f32 v176, v176, v112, v144
	v_fma_f32 v177, v177, v113, v145
	v_fma_f32 v178, v178, v114, v146
	v_fma_f32 v179, v179, v115, v147
; DI void ln_finish(const Params& p, float* __restrict__ pr, const float4 (&v)[8], int lane) {
;   float s = 0.f;
; #pragma unroll
;   for (int i = 0; i < 8; ++i) s += v[i].x + v[i].y + v[i].z + v[i].w;
; #pragma unroll
;   for (int o = 32; o >= 1; o >>= 1) s += __shfl_xor(s, o);
;   const float mu = s * (1.f / 2048.f);
;   float q = 0.f;
; #pragma unroll
;   for (int i = 0; i < 8; ++i) {
;     const float a = v[i].x - mu, b = v[i].y - mu, c = v[i].z - mu, d = v[i].w - mu;
;     q += a * a + b * b + c * c + d * d;
;   }
; #pragma unroll
;   for (int o = 32; o >= 1; o >>= 1) q += __shfl_xor(q, o);
;   const float rstd = rsqrtf(q * (1.f / 2048.f) + EPSV);
; #pragma unroll
;   for (int i = 0; i < 8; ++i) {
;     const int c0 = (i * 64 + lane) * 4;
;     const float4 g = *reinterpret_cast<const float4*>(p.ln_g + c0);
;     const float4 bb = *reinterpret_cast<const float4*>(p.ln_b + c0);
;     float4 o;
;     o.x = (v[i].x - mu) * rstd * g.x + bb.x;
;     o.y = (v[i].y - mu) * rstd * g.y + bb.y;
;     o.z = (v[i].z - mu) * rstd * g.z + bb.z;
;     o.w = (v[i].w - mu) * rstd * g.w + bb.w;
;     *reinterpret_cast<float4*>(pr + c0) = o;
; __device__ void phaseD_handoff(const Params& p, unsigned char* smem) {
;     ...
;     for (int k = 0; k < 4; ++k) {
;       float* pa = p.out + O_Y + (size_t)(row0 + k) * 2048;
;       float* pb = p.out + O_Y + (size_t)(row0 + 4 + k) * 2048;
;       float4 va[8], vb[8];
; #pragma unroll
;       for (int i = 0; i < 8; ++i) va[i] = *reinterpret_cast<const float4*>(pa + (i * 64 + lane) * 4);
; #pragma unroll
;       for (int i = 0; i < 8; ++i) vb[i] = *reinterpret_cast<const float4*>(pb + (i * 64 + lane) * 4);
;       ln_finish(p, pa, va, lane);
;       ln_finish(p, pb, vb, lane);
	v_fma_f32 v180, v180, v116, v148
	v_fma_f32 v181, v181, v117, v149
	v_fma_f32 v182, v182, v118, v150
	v_fma_f32 v183, v183, v119, v151
	v_fma_f32 v184, v184, v120, v152
	v_fma_f32 v185, v185, v121, v153
	v_fma_f32 v186, v186, v122, v154
	v_fma_f32 v187, v187, v123, v155
	v_fma_f32 v188, v188, v124, v156
	v_fma_f32 v189, v189, v125, v157
	v_fma_f32 v190, v190, v126, v158
	v_fma_f32 v191, v191, v127, v159
	v_fma_f32 v192, v192, v128, v160
	v_fma_f32 v193, v193, v129, v161
	v_fma_f32 v194, v194, v130, v162
	v_fma_f32 v195, v195, v131, v163
	v_fma_f32 v196, v196, v132, v164
	v_fma_f32 v197, v197, v133, v165
	v_fma_f32 v198, v198, v134, v166
	v_fma_f32 v199, v199, v135, v167
	v_fma_f32 v200, v200, v136, v168
	v_fma_f32 v201, v201, v137, v169
	v_fma_f32 v202, v202, v138, v170
	v_fma_f32 v203, v203, v139, v171
	v_fma_f32 v204, v204, v140, v172
	v_fma_f32 v205, v205, v141, v173
	v_fma_f32 v206, v206, v142, v174
	v_fma_f32 v207, v207, v143, v175
	global_store_dwordx4 v[96:97], v[176:179], off
	global_store_dwordx4 v[96:97], v[180:183], off offset:1024
	global_store_dwordx4 v[96:97], v[184:187], off offset:2048
	global_store_dwordx4 v[96:97], v[188:191], off offset:3072
	global_store_dwordx4 v[98:99], v[192:195], off
	global_store_dwordx4 v[98:99], v[196:199], off offset:1024
	global_store_dwordx4 v[98:99], v[200:203], off offset:2048
	global_store_dwordx4 v[98:99], v[204:207], off offset:3072
	s_waitcnt vmcnt(24)
	v_add_f32_e32 v208, v0, v4
	v_add_f32_e32 v209, v1, v5
	v_add_f32_e32 v210, v2, v6
	v_add_f32_e32 v211, v3, v7
	v_add_f32_e32 v208, v8, v208
	v_add_f32_e32 v209, v9, v209
	v_add_f32_e32 v210, v10, v210
	v_add_f32_e32 v211, v11, v211
	v_add_f32_e32 v208, v12, v208
	v_add_f32_e32 v209, v13, v209
	v_add_f32_e32 v210, v14, v210
	v_add_f32_e32 v211, v15, v211
	v_add_f32_e32 v208, v16, v208
	v_add_f32_e32 v209, v17, v209
	v_add_f32_e32 v210, v18, v210
	v_add_f32_e32 v211, v19, v211
	v_add_f32_e32 v208, v20, v208
	v_add_f32_e32 v209, v21, v209
	v_add_f32_e32 v210, v22, v210
	v_add_f32_e32 v211, v23, v211
	v_add_f32_e32 v208, v24, v208
	v_add_f32_e32 v209, v25, v209
	v_add_f32_e32 v210, v26, v210
	v_add_f32_e32 v211, v27, v211
	v_add_f32_e32 v208, v28, v208
	v_add_f32_e32 v209, v29, v209
	v_add_f32_e32 v210, v30, v210
	v_add_f32_e32 v211, v31, v211
	v_add_f32_e32 v208, v208, v209
	v_add_f32_e32 v210, v210, v211
	v_add_f32_e32 v208, v208, v210
	s_nop 1
	v_add_f32_dpp v208, v208, v208 quad_perm:[1,0,3,2] row_mask:0xf bank_mask:0xf
	s_nop 1
	v_add_f32_dpp v208, v208, v208 quad_perm:[2,3,0,1] row_mask:0xf bank_mask:0xf
	s_nop 1
	v_add_f32_dpp v208, v208, v208 row_half_mirror row_mask:0xf bank_mask:0xf
	s_nop 1
	v_add_f32_dpp v208, v208, v208 row_mirror row_mask:0xf bank_mask:0xf
	s_nop 1
	v_readlane_b32 s16, v208, 0
	v_readlane_b32 s17, v208, 16
	v_readlane_b32 s18, v208, 32
	v_readlane_b32 s19, v208, 48
	s_nop 1
	v_mov_b32_e32 v208, s16
	v_add_f32_e32 v208, s17, v208
	v_add_f32_e32 v208, s18, v208
	v_add_f32_e32 v208, s19, v208
	v_mul_f32_e32 v212, 0x3a000000, v208
	v_sub_f32_e32 v0, v0, v212
	v_sub_f32_e32 v1, v1, v212
	v_sub_f32_e32 v2, v2, v212
	v_sub_f32_e32 v3, v3, v212
	v_sub_f32_e32 v4, v4, v212
	v_sub_f32_e32 v5, v5, v212
	v_sub_f32_e32 v6, v6, v212
	v_sub_f32_e32 v7, v7, v212
	v_sub_f32_e32 v8, v8, v212
	v_sub_f32_e32 v9, v9, v212
	v_sub_f32_e32 v10, v10, v212
	v_sub_f32_e32 v11, v11, v212
	v_sub_f32_e32 v12, v12, v212
	v_sub_f32_e32 v13, v13, v212
	v_sub_f32_e32 v14, v14, v212
	v_sub_f32_e32 v15, v15, v212
	v_sub_f32_e32 v16, v16, v212
	v_sub_f32_e32 v17, v17, v212
	v_sub_f32_e32 v18, v18, v212
	v_sub_f32_e32 v19, v19, v212
	v_sub_f32_e32 v20, v20, v212
	v_sub_f32_e32 v21, v21, v212
	v_sub_f32_e32 v22, v22, v212
	v_sub_f32_e32 v23, v23, v212
	v_sub_f32_e32 v24, v24, v212
	v_sub_f32_e32 v25, v25, v212
	v_sub_f32_e32 v26, v26, v212
	v_sub_f32_e32 v27, v27, v212
	v_sub_f32_e32 v28, v28, v212
	v_sub_f32_e32 v29, v29, v212
	v_sub_f32_e32 v30, v30, v212
	v_sub_f32_e32 v31, v31, v212
	v_mul_f32_e32 v208, v0, v0
	v_mul_f32_e32 v209, v1, v1
	v_mul_f32_e32 v210, v2, v2
	v_mul_f32_e32 v211, v3, v3
	v_fmac_f32_e32 v208, v4, v4
	v_fmac_f32_e32 v209, v5, v5
	v_fmac_f32_e32 v210, v6, v6
	v_fmac_f32_e32 v211, v7, v7
	v_fmac_f32_e32 v208, v8, v8
	v_fmac_f32_e32 v209, v9, v9
	v_fmac_f32_e32 v210, v10, v10
	v_fmac_f32_e32 v211, v11, v11
	v_fmac_f32_e32 v208, v12, v12
	v_fmac_f32_e32 v209, v13, v13
	v_fmac_f32_e32 v210, v14, v14
	v_fmac_f32_e32 v211, v15, v15
	v_fmac_f32_e32 v208, v16, v16
	v_fmac_f32_e32 v209, v17, v17
	v_fmac_f32_e32 v210, v18, v18
	v_fmac_f32_e32 v211, v19, v19
	v_fmac_f32_e32 v208, v20, v20
	v_fmac_f32_e32 v209, v21, v21
	v_fmac_f32_e32 v210, v22, v22
	v_fmac_f32_e32 v211, v23, v23
	v_fmac_f32_e32 v208, v24, v24
	v_fmac_f32_e32 v209, v25, v25
	v_fmac_f32_e32 v210, v26, v26
	v_fmac_f32_e32 v211, v27, v27
	v_fmac_f32_e32 v208, v28, v28
	v_fmac_f32_e32 v209, v29, v29
	v_fmac_f32_e32 v210, v30, v30
	v_fmac_f32_e32 v211, v31, v31
	v_add_f32_e32 v208, v208, v209
	v_add_f32_e32 v210, v210, v211
	v_add_f32_e32 v208, v208, v210
	s_nop 1
	v_add_f32_dpp v208, v208, v208 quad_perm:[1,0,3,2] row_mask:0xf bank_mask:0xf
	s_nop 1
	v_add_f32_dpp v208, v208, v208 quad_perm:[2,3,0,1] row_mask:0xf bank_mask:0xf
	s_nop 1
	v_add_f32_dpp v208, v208, v208 row_half_mirror row_mask:0xf bank_mask:0xf
	s_nop 1
	v_add_f32_dpp v208, v208, v208 row_mirror row_mask:0xf bank_mask:0xf
	s_nop 1
	v_readlane_b32 s16, v208, 0
	v_readlane_b32 s17, v208, 16
	v_readlane_b32 s18, v208, 32
	v_readlane_b32 s19, v208, 48
	s_nop 1
	v_mov_b32_e32 v208, s16
	v_add_f32_e32 v208, s17, v208
	v_add_f32_e32 v208, s18, v208
	v_add_f32_e32 v208, s19, v208
	v_mov_b32_e32 v213, 0x3727c5ac
; DI void ln_finish(const Params& p, float* __restrict__ pr, const float4 (&v)[8], int lane) {
;     ...
;   const float rstd = rsqrtf(q * (1.f / 2048.f) + EPSV);
; #pragma unroll
;   for (int i = 0; i < 8; ++i) {
;     const int c0 = (i * 64 + lane) * 4;
;     const float4 g = *reinterpret_cast<const float4*>(p.ln_g + c0);
;     const float4 bb = *reinterpret_cast<const float4*>(p.ln_b + c0);
;     float4 o;
;     o.x = (v[i].x - mu) * rstd * g.x + bb.x;
;     o.y = (v[i].y - mu) * rstd * g.y + bb.y;
;     o.z = (v[i].z - mu) * rstd * g.z + bb.z;
;     o.w = (v[i].w - mu) * rstd * g.w + bb.w;
;     *reinterpret_cast<float4*>(pr + c0) = o;
	v_fmac_f32_e32 v213, 0x3a000000, v208
	v_rsq_f32_e32 v213, v213
	s_nop 0
	v_mul_f32_e32 v0, v0, v213
	v_mul_f32_e32 v1, v1, v213
	v_mul_f32_e32 v2, v2, v213
	v_mul_f32_e32 v3, v3, v213
	v_mul_f32_e32 v4, v4, v213
	v_mul_f32_e32 v5, v5, v213
	v_mul_f32_e32 v6, v6, v213
	v_mul_f32_e32 v7, v7, v213
	v_mul_f32_e32 v8, v8, v213
	v_mul_f32_e32 v9, v9, v213
	v_mul_f32_e32 v10, v10, v213
	v_mul_f32_e32 v11, v11, v213
	v_mul_f32_e32 v12, v12, v213
	v_mul_f32_e32 v13, v13, v213
	v_mul_f32_e32 v14, v14, v213
	v_mul_f32_e32 v15, v15, v213
	v_mul_f32_e32 v16, v16, v213
	v_mul_f32_e32 v17, v17, v213
	v_mul_f32_e32 v18, v18, v213
	v_mul_f32_e32 v19, v19, v213
	v_mul_f32_e32 v20, v20, v213
	v_mul_f32_e32 v21, v21, v213
	v_mul_f32_e32 v22, v22, v213
	v_mul_f32_e32 v23, v23, v213
	v_mul_f32_e32 v24, v24, v213
	v_mul_f32_e32 v25, v25, v213
	v_mul_f32_e32 v26, v26, v213
	v_mul_f32_e32 v27, v27, v213
	v_mul_f32_e32 v28, v28, v213
	v_mul_f32_e32 v29, v29, v213
	v_mul_f32_e32 v30, v30, v213
	v_mul_f32_e32 v31, v31, v213
	v_fma_f32 v0, v0, v112, v144
	v_fma_f32 v1, v1, v113, v145
	v_fma_f32 v2, v2, v114, v146
	v_fma_f32 v3, v3, v115, v147
	v_fma_f32 v4, v4, v116, v148
	v_fma_f32 v5, v5, v117, v149
	v_fma_f32 v6, v6, v118, v150
	v_fma_f32 v7, v7, v119, v151
	v_fma_f32 v8, v8, v120, v152
	v_fma_f32 v9, v9, v121, v153
	v_fma_f32 v10, v10, v122, v154
	v_fma_f32 v11, v11, v123, v155
	v_fma_f32 v12, v12, v124, v156
	v_fma_f32 v13, v13, v125, v157
	v_fma_f32 v14, v14, v126, v158
	v_fma_f32 v15, v15, v127, v159
	v_fma_f32 v16, v16, v128, v160
	v_fma_f32 v17, v17, v129, v161
	v_fma_f32 v18, v18, v130, v162
	v_fma_f32 v19, v19, v131, v163
	v_fma_f32 v20, v20, v132, v164
	v_fma_f32 v21, v21, v133, v165
	v_fma_f32 v22, v22, v134, v166
	v_fma_f32 v23, v23, v135, v167
	v_fma_f32 v24, v24, v136, v168
	v_fma_f32 v25, v25, v137, v169
	v_fma_f32 v26, v26, v138, v170
	v_fma_f32 v27, v27, v139, v171
	v_fma_f32 v28, v28, v140, v172
	v_fma_f32 v29, v29, v141, v173
	v_fma_f32 v30, v30, v142, v174
	v_fma_f32 v31, v31, v143, v175
	global_store_dwordx4 v[88:89], v[0:3], off
	global_store_dwordx4 v[88:89], v[4:7], off offset:1024
	global_store_dwordx4 v[88:89], v[8:11], off offset:2048
	global_store_dwordx4 v[88:89], v[12:15], off offset:3072
	global_store_dwordx4 v[90:91], v[16:19], off
	global_store_dwordx4 v[90:91], v[20:23], off offset:1024
	global_store_dwordx4 v[90:91], v[24:27], off offset:2048
	global_store_dwordx4 v[90:91], v[28:31], off offset:3072
	s_waitcnt vmcnt(16)
; DI void ln_finish(const Params& p, float* __restrict__ pr, const float4 (&v)[8], int lane) {
;   float s = 0.f;
; #pragma unroll
;   for (int i = 0; i < 8; ++i) s += v[i].x + v[i].y + v[i].z + v[i].w;
; #pragma unroll
;   for (int o = 32; o >= 1; o >>= 1) s += __shfl_xor(s, o);
;   const float mu = s * (1.f / 2048.f);
;   float q = 0.f;
; #pragma unroll
;   for (int i = 0; i < 8; ++i) {
;     const float a = v[i].x - mu, b = v[i].y - mu, c = v[i].z - mu, d = v[i].w - mu;
;     q += a * a + b * b + c * c + d * d;
;   }
; #pragma unroll
;   for (int o = 32; o >= 1; o >>= 1) q += __shfl_xor(q, o);
;   const float rstd = rsqrtf(q * (1.f / 2048.f) + EPSV);
; #pragma unroll
;   for (int i = 0; i < 8; ++i) {
;     const int c0 = (i * 64 + lane) * 4;
;     const float4 g = *reinterpret_cast<const float4*>(p.ln_g + c0);
;     const float4 bb = *reinterpret_cast<const float4*>(p.ln_b + c0);
;     float4 o;
;     o.x = (v[i].x - mu) * rstd * g.x + bb.x;
;     o.y = (v[i].y - mu) * rstd * g.y + bb.y;
;     o.z = (v[i].z - mu) * rstd * g.z + bb.z;
;     o.w = (v[i].w - mu) * rstd * g.w + bb.w;
;     *reinterpret_cast<float4*>(pr + c0) = o;
; __device__ void phaseD_handoff(const Params& p, unsigned char* smem) {
;     ...
; #pragma unroll 1
;     for (int k = 0; k < 4; ++k) {
;       float* pa = p.out + O_Y + (size_t)(row0 + k) * 2048;
;       float* pb = p.out + O_Y + (size_t)(row0 + 4 + k) * 2048;
;       float4 va[8], vb[8];
; #pragma unroll
;       for (int i = 0; i < 8; ++i) va[i] = *reinterpret_cast<const float4*>(pa + (i * 64 + lane) * 4);
; #pragma unroll
;       for (int i = 0; i < 8; ++i) vb[i] = *reinterpret_cast<const float4*>(pb + (i * 64 + lane) * 4);
;       ln_finish(p, pa, va, lane);
;       ln_finish(p, pb, vb, lane);
;     }
	v_add_f32_e32 v208, v32, v36
	v_add_f32_e32 v209, v33, v37
	v_add_f32_e32 v210, v34, v38
	v_add_f32_e32 v211, v35, v39
	v_add_f32_e32 v208, v40, v208
	v_add_f32_e32 v209, v41, v209
	v_add_f32_e32 v210, v42, v210
	v_add_f32_e32 v211, v43, v211
	v_add_f32_e32 v208, v44, v208
	v_add_f32_e32 v209, v45, v209
	v_add_f32_e32 v210, v46, v210
	v_add_f32_e32 v211, v47, v211
	v_add_f32_e32 v208, v48, v208
	v_add_f32_e32 v209, v49, v209
	v_add_f32_e32 v210, v50, v210
	v_add_f32_e32 v211, v51, v211
	v_add_f32_e32 v208, v52, v208
	v_add_f32_e32 v209, v53, v209
	v_add_f32_e32 v210, v54, v210
	v_add_f32_e32 v211, v55, v211
	v_add_f32_e32 v208, v56, v208
	v_add_f32_e32 v209, v57, v209
	v_add_f32_e32 v210, v58, v210
	v_add_f32_e32 v211, v59, v211
	v_add_f32_e32 v208, v60, v208
	v_add_f32_e32 v209, v61, v209
	v_add_f32_e32 v210, v62, v210
	v_add_f32_e32 v211, v63, v211
	v_add_f32_e32 v208, v208, v209
	v_add_f32_e32 v210, v210, v211
	v_add_f32_e32 v208, v208, v210
	s_nop 1
	v_add_f32_dpp v208, v208, v208 quad_perm:[1,0,3,2] row_mask:0xf bank_mask:0xf
	s_nop 1
	v_add_f32_dpp v208, v208, v208 quad_perm:[2,3,0,1] row_mask:0xf bank_mask:0xf
	s_nop 1
	v_add_f32_dpp v208, v208, v208 row_half_mirror row_mask:0xf bank_mask:0xf
	s_nop 1
	v_add_f32_dpp v208, v208, v208 row_mirror row_mask:0xf bank_mask:0xf
	s_nop 1
	v_readlane_b32 s16, v208, 0
	v_readlane_b32 s17, v208, 16
	v_readlane_b32 s18, v208, 32
	v_readlane_b32 s19, v208, 48
	s_nop 1
	v_mov_b32_e32 v208, s16
	v_add_f32_e32 v208, s17, v208
	v_add_f32_e32 v208, s18, v208
	v_add_f32_e32 v208, s19, v208
	v_mul_f32_e32 v212, 0x3a000000, v208
	v_sub_f32_e32 v32, v32, v212
	v_sub_f32_e32 v33, v33, v212
	v_sub_f32_e32 v34, v34, v212
	v_sub_f32_e32 v35, v35, v212
	v_sub_f32_e32 v36, v36, v212
	v_sub_f32_e32 v37, v37, v212
	v_sub_f32_e32 v38, v38, v212
	v_sub_f32_e32 v39, v39, v212
	v_sub_f32_e32 v40, v40, v212
	v_sub_f32_e32 v41, v41, v212
	v_sub_f32_e32 v42, v42, v212
	v_sub_f32_e32 v43, v43, v212
	v_sub_f32_e32 v44, v44, v212
	v_sub_f32_e32 v45, v45, v212
	v_sub_f32_e32 v46, v46, v212
	v_sub_f32_e32 v47, v47, v212
	v_sub_f32_e32 v48, v48, v212
	v_sub_f32_e32 v49, v49, v212
	v_sub_f32_e32 v50, v50, v212
	v_sub_f32_e32 v51, v51, v212
	v_sub_f32_e32 v52, v52, v212
	v_sub_f32_e32 v53, v53, v212
	v_sub_f32_e32 v54, v54, v212
	v_sub_f32_e32 v55, v55, v212
	v_sub_f32_e32 v56, v56, v212
	v_sub_f32_e32 v57, v57, v212
	v_sub_f32_e32 v58, v58, v212
	v_sub_f32_e32 v59, v59, v212
	v_sub_f32_e32 v60, v60, v212
	v_sub_f32_e32 v61, v61, v212
	v_sub_f32_e32 v62, v62, v212
	v_sub_f32_e32 v63, v63, v212
	v_mul_f32_e32 v208, v32, v32
	v_mul_f32_e32 v209, v33, v33
	v_mul_f32_e32 v210, v34, v34
	v_mul_f32_e32 v211, v35, v35
	v_fmac_f32_e32 v208, v36, v36
	v_fmac_f32_e32 v209, v37, v37
	v_fmac_f32_e32 v210, v38, v38
	v_fmac_f32_e32 v211, v39, v39
	v_fmac_f32_e32 v208, v40, v40
	v_fmac_f32_e32 v209, v41, v41
	v_fmac_f32_e32 v210, v42, v42
	v_fmac_f32_e32 v211, v43, v43
	v_fmac_f32_e32 v208, v44, v44
	v_fmac_f32_e32 v209, v45, v45
	v_fmac_f32_e32 v210, v46, v46
	v_fmac_f32_e32 v211, v47, v47
	v_fmac_f32_e32 v208, v48, v48
	v_fmac_f32_e32 v209, v49, v49
	v_fmac_f32_e32 v210, v50, v50
	v_fmac_f32_e32 v211, v51, v51
	v_fmac_f32_e32 v208, v52, v52
	v_fmac_f32_e32 v209, v53, v53
	v_fmac_f32_e32 v210, v54, v54
	v_fmac_f32_e32 v211, v55, v55
	v_fmac_f32_e32 v208, v56, v56
	v_fmac_f32_e32 v209, v57, v57
	v_fmac_f32_e32 v210, v58, v58
	v_fmac_f32_e32 v211, v59, v59
	v_fmac_f32_e32 v208, v60, v60
	v_fmac_f32_e32 v209, v61, v61
	v_fmac_f32_e32 v210, v62, v62
	v_fmac_f32_e32 v211, v63, v63
	v_add_f32_e32 v208, v208, v209
	v_add_f32_e32 v210, v210, v211
	v_add_f32_e32 v208, v208, v210
	s_nop 1
	v_add_f32_dpp v208, v208, v208 quad_perm:[1,0,3,2] row_mask:0xf bank_mask:0xf
	s_nop 1
	v_add_f32_dpp v208, v208, v208 quad_perm:[2,3,0,1] row_mask:0xf bank_mask:0xf
	s_nop 1
	v_add_f32_dpp v208, v208, v208 row_half_mirror row_mask:0xf bank_mask:0xf
	s_nop 1
	v_add_f32_dpp v208, v208, v208 row_mirror row_mask:0xf bank_mask:0xf
	s_nop 1
	v_readlane_b32 s16, v208, 0
	v_readlane_b32 s17, v208, 16
	v_readlane_b32 s18, v208, 32
	v_readlane_b32 s19, v208, 48
	s_nop 1
	v_mov_b32_e32 v208, s16
	v_add_f32_e32 v208, s17, v208
	v_add_f32_e32 v208, s18, v208
	v_add_f32_e32 v208, s19, v208
	v_mov_b32_e32 v213, 0x3727c5ac
	v_fmac_f32_e32 v213, 0x3a000000, v208
	v_rsq_f32_e32 v213, v213
	s_nop 0
	v_mul_f32_e32 v32, v32, v213
	v_mul_f32_e32 v33, v33, v213
	v_mul_f32_e32 v34, v34, v213
	v_mul_f32_e32 v35, v35, v213
	v_mul_f32_e32 v36, v36, v213
	v_mul_f32_e32 v37, v37, v213
	v_mul_f32_e32 v38, v38, v213
	v_mul_f32_e32 v39, v39, v213
	v_mul_f32_e32 v40, v40, v213
	v_mul_f32_e32 v41, v41, v213
	v_mul_f32_e32 v42, v42, v213
	v_mul_f32_e32 v43, v43, v213
	v_mul_f32_e32 v44, v44, v213
	v_mul_f32_e32 v45, v45, v213
	v_mul_f32_e32 v46, v46, v213
	v_mul_f32_e32 v47, v47, v213
	v_mul_f32_e32 v48, v48, v213
	v_mul_f32_e32 v49, v49, v213
	v_mul_f32_e32 v50, v50, v213
	v_mul_f32_e32 v51, v51, v213
	v_mul_f32_e32 v52, v52, v213
	v_mul_f32_e32 v53, v53, v213
	v_mul_f32_e32 v54, v54, v213
	v_mul_f32_e32 v55, v55, v213
	v_mul_f32_e32 v56, v56, v213
	v_mul_f32_e32 v57, v57, v213
	v_mul_f32_e32 v58, v58, v213
	v_mul_f32_e32 v59, v59, v213
	v_mul_f32_e32 v60, v60, v213
	v_mul_f32_e32 v61, v61, v213
	v_mul_f32_e32 v62, v62, v213
	v_mul_f32_e32 v63, v63, v213
	v_fma_f32 v32, v32, v112, v144
	v_fma_f32 v33, v33, v113, v145
	v_fma_f32 v34, v34, v114, v146
	v_fma_f32 v35, v35, v115, v147
	v_fma_f32 v36, v36, v116, v148
	v_fma_f32 v37, v37, v117, v149
	v_fma_f32 v38, v38, v118, v150
	v_fma_f32 v39, v39, v119, v151
	v_fma_f32 v40, v40, v120, v152
	v_fma_f32 v41, v41, v121, v153
	v_fma_f32 v42, v42, v122, v154
	v_fma_f32 v43, v43, v123, v155
	v_fma_f32 v44, v44, v124, v156
	v_fma_f32 v45, v45, v125, v157
	v_fma_f32 v46, v46, v126, v158
	v_fma_f32 v47, v47, v127, v159
	v_fma_f32 v48, v48, v128, v160
	v_fma_f32 v49, v49, v129, v161
	v_fma_f32 v50, v50, v130, v162
	v_fma_f32 v51, v51, v131, v163
	v_fma_f32 v52, v52, v132, v164
	v_fma_f32 v53, v53, v133, v165
	v_fma_f32 v54, v54, v134, v166
	v_fma_f32 v55, v55, v135, v167
	v_fma_f32 v56, v56, v136, v168
	v_fma_f32 v57, v57, v137, v169
	v_fma_f32 v58, v58, v138, v170
	v_fma_f32 v59, v59, v139, v171
	v_fma_f32 v60, v60, v140, v172
	v_fma_f32 v61, v61, v141, v173
	v_fma_f32 v62, v62, v142, v174
	v_fma_f32 v63, v63, v143, v175
	global_store_dwordx4 v[92:93], v[32:35], off
	global_store_dwordx4 v[92:93], v[36:39], off offset:1024
	global_store_dwordx4 v[92:93], v[40:43], off offset:2048
	global_store_dwordx4 v[92:93], v[44:47], off offset:3072
	global_store_dwordx4 v[94:95], v[48:51], off
	global_store_dwordx4 v[94:95], v[52:55], off offset:1024
	global_store_dwordx4 v[94:95], v[56:59], off offset:2048
	global_store_dwordx4 v[94:95], v[60:63], off offset:3072
	s_mov_b64 s[4:5], 0
	s_branch .LBB0_659
